# attention K-loops: rescale only when a row max exceeds the running reference by >4 (log2), MLA loop folds the reference subtraction into the QK MFMA accumulator init and uses a leaner softmax/PV block
# speedup vs baseline: 1.2971x; 1.0260x over previous
; #define MFMA(a, b, c) __builtin_amdgcn_mfma_f32_32x32x16_bf16((a), (b), (c), 0, 0, 0)
; #define GLOAD(t) { const int pos0_ = TILE_POS(t); \
;     rk0 = *(const uint4*)(K + (size_t)(pos0_ + kr0) * ldk + kc0); rk1 = *(const uint4*)(K + (size_t)(pos0_ + kr1) * ldk + kc1); \
;     if (NKC == 3) rk2 = *(const uint4*)(K + (size_t)(pos0_ + kr2) * ldk + kc2); \
;     rv0 = *(const uint4*)(Vt + (size_t)vd0 * SEQA + pos0_ + vk0); rv1 = *(const uint4*)(Vt + (size_t)(vd0 + 32) * SEQA + pos0_ + vk0); }
; #define GLOAD(t) { const int pos0_ = (t) * 64; \
;     rk0 = *(const uint4*)(K + (size_t)(pos0_ + kr0) * ldk + kc0); rk1 = *(const uint4*)(K + (size_t)(pos0_ + kr1) * ldk + kc1); \
;     if (NKC == 3) rk2 = *(const uint4*)(K + (size_t)(pos0_ + kr2) * ldk + kc2); \
;     rv0 = *(const uint4*)(Vt + (size_t)vd0 * SEQA + pos0_ + vk0); rv1 = *(const uint4*)(Vt + (size_t)(vd0 + 32) * SEQA + pos0_ + vk0); }
; template <int DK>
; DI void attn_item2(const u16* __restrict__ Q, int ldq, const u16* __restrict__ K, int ldk, const u16* __restrict__ Vt, int nTiles,
;                    u16* __restrict__ Gp, const u16* __restrict__ Zp, char* smem, int tid) {
;     ...
;   for (int t = 0; t < nTiles; t++) {
;     const int buf = t & 1;
;     if (t + 1 < nTiles) GLOAD(t + 1);
; #pragma unroll
;     for (int kb = 0; kb < 2; kb++) {
;       f32x16 s0, s1;
; #pragma unroll
;       for (int i = 0; i < 16; i++) { s0[i] = 0.f; s1[i] = 0.f; }
; #pragma unroll
;       for (int ks = 0; ks < KS; ks++) {
;         bf16x8 a = *(const bf16x8*)&Ks[buf][kb * 32 + r][ks * 16 + h * 8];
;         s0 = MFMA(a, qf[0][ks], s0);
;         s1 = MFMA(a, qf[1][ks], s1);
;       }
;       bf16x8 pf0[2], pf1[2];
;     ...
;       SOFTMAX_STEP(s0, m_run0, l_run0, o[0], pf0)
;       SOFTMAX_STEP(s1, m_run1, l_run1, o[1], pf1)
.LBB0_862:
	v_lshl_add_u64 v[14:15], v[198:199], 0, v[204:205]
	s_mov_b32 s8, 0xf240000
	v_add_co_u32_e32 v10, vcc, s8, v14
	s_mov_b32 s8, 0xf284000
	s_nop 0
	v_addc_co_u32_e32 v11, vcc, 0, v15, vcc
	v_add_co_u32_e32 v14, vcc, s8, v14
	v_lshl_add_u64 v[2:3], v[200:201], 0, v[204:205]
	v_lshl_add_u64 v[6:7], v[202:203], 0, v[204:205]
	v_addc_co_u32_e32 v15, vcc, 0, v15, vcc
	global_load_dwordx4 v[2:5], v[2:3], off
	s_and_b32 s3, s2, 1
	global_load_dwordx4 v[6:9], v[6:7], off
	s_mul_i32 s8, s3, 0x2400
	global_load_dwordx4 v[10:13], v[10:11], off offset:128
	v_add_u32_e32 v230, s8, v225
	global_load_dwordx4 v[144:147], v[14:15], off offset:128
	ds_read_b128 v[80:83], v230
	ds_read_b128 v[232:235], v230 offset:32
	s_waitcnt vmcnt(11) lgkmcnt(1)
	v_mfma_f32_32x32x16_bf16 v[96:111], v[80:83], v[132:135], 0
	s_waitcnt vmcnt(7)
	v_mfma_f32_32x32x16_bf16 v[80:95], v[80:83], v[140:143], 0
	s_waitcnt lgkmcnt(0)
	v_mfma_f32_32x32x16_bf16 v[96:111], v[232:235], v[124:127], v[96:111]
	s_waitcnt vmcnt(6)
	v_mfma_f32_32x32x16_bf16 v[80:95], v[232:235], v[136:139], v[80:95]
	ds_read_b128 v[232:235], v230 offset:64
	s_waitcnt lgkmcnt(0)
	v_mfma_f32_32x32x16_bf16 v[96:111], v[232:235], v[120:123], v[96:111]
	s_waitcnt vmcnt(5)
	v_mfma_f32_32x32x16_bf16 v[80:95], v[232:235], v[128:131], v[80:95]
	ds_read_b128 v[232:235], v230 offset:96
	s_waitcnt lgkmcnt(0)
	v_mfma_f32_32x32x16_bf16 v[96:111], v[232:235], v[112:115], v[96:111]
	s_waitcnt vmcnt(4)
	v_mfma_f32_32x32x16_bf16 v[80:95], v[232:235], v[116:119], v[80:95]
	s_nop 9
	v_max3_f32 v14, v96, v97, v98
	v_max3_f32 v15, v99, v100, v101
	v_max3_f32 v231, v102, v103, v104
	v_max3_f32 v232, v105, v106, v107
	v_max3_f32 v233, v108, v109, v110
	v_max3_f32 v14, v14, v15, v231
	v_max3_f32 v232, v232, v233, v111
	v_max_f32_e32 v14, v14, v232
	v_mov_b32_e32 v15, v14
	s_nop 1
	v_permlane32_swap_b32_e32 v14, v15
	v_max_f32_e32 v15, v15, v15
	v_max_f32_e32 v14, v14, v14
	v_max_f32_e32 v14, v14, v15
	v_add_f32_e32 v15, 4.0, v191
	v_cmp_gt_f32_e32 vcc, v14, v15
	s_cbranch_vccz .LBB0_864
	v_max_f32_e32 v14, v14, v14
	v_max_f32_e32 v15, v191, v191
	v_max_f32_e32 v15, v15, v14
	v_sub_f32_e32 v14, v191, v15
	v_exp_f32_e32 v14, v14
	v_mov_b32_e32 v191, v15
	v_pk_mul_f32 v[78:79], v[78:79], v[14:15] op_sel_hi:[1,0]
	v_pk_mul_f32 v[76:77], v[76:77], v[14:15] op_sel_hi:[1,0]
	v_pk_mul_f32 v[74:75], v[74:75], v[14:15] op_sel_hi:[1,0]
	v_pk_mul_f32 v[72:73], v[72:73], v[14:15] op_sel_hi:[1,0]
	v_pk_mul_f32 v[70:71], v[70:71], v[14:15] op_sel_hi:[1,0]
	v_pk_mul_f32 v[68:69], v[68:69], v[14:15] op_sel_hi:[1,0]
	v_pk_mul_f32 v[66:67], v[66:67], v[14:15] op_sel_hi:[1,0]
	v_pk_mul_f32 v[64:65], v[64:65], v[14:15] op_sel_hi:[1,0]
	v_pk_mul_f32 v[62:63], v[62:63], v[14:15] op_sel_hi:[1,0]
	v_pk_mul_f32 v[60:61], v[60:61], v[14:15] op_sel_hi:[1,0]
	v_pk_mul_f32 v[58:59], v[58:59], v[14:15] op_sel_hi:[1,0]
	v_pk_mul_f32 v[56:57], v[56:57], v[14:15] op_sel_hi:[1,0]
	v_pk_mul_f32 v[54:55], v[54:55], v[14:15] op_sel_hi:[1,0]
	v_pk_mul_f32 v[52:53], v[52:53], v[14:15] op_sel_hi:[1,0]
	v_pk_mul_f32 v[50:51], v[50:51], v[14:15] op_sel_hi:[1,0]
	v_pk_mul_f32 v[48:49], v[48:49], v[14:15] op_sel_hi:[1,0]
	v_mul_f32_e32 v229, v229, v14
.LBB0_864:
	v_max3_f32 v14, v80, v81, v82
	v_max3_f32 v15, v83, v84, v85
	v_max3_f32 v231, v86, v87, v88
	v_max3_f32 v232, v89, v90, v91
	v_max3_f32 v233, v92, v93, v94
	v_max3_f32 v14, v14, v15, v231
	v_max3_f32 v232, v232, v233, v95
	v_max_f32_e32 v14, v14, v232
	v_mov_b32_e32 v15, v14
	s_nop 1
	v_permlane32_swap_b32_e32 v14, v15
	v_max_f32_e32 v15, v15, v15
	v_max_f32_e32 v14, v14, v14
	v_max_f32_e32 v14, v14, v15
	v_add_f32_e32 v15, 4.0, v189
	v_cmp_gt_f32_e32 vcc, v14, v15
	s_cbranch_vccz .LBB0_866
	v_max_f32_e32 v14, v14, v14
	v_max_f32_e32 v15, v189, v189
	v_max_f32_e32 v15, v15, v14
	v_sub_f32_e32 v14, v189, v15
	v_exp_f32_e32 v14, v14
	v_mov_b32_e32 v189, v15
	v_pk_mul_f32 v[46:47], v[46:47], v[14:15] op_sel_hi:[1,0]
	v_pk_mul_f32 v[44:45], v[44:45], v[14:15] op_sel_hi:[1,0]
	v_pk_mul_f32 v[42:43], v[42:43], v[14:15] op_sel_hi:[1,0]
	v_pk_mul_f32 v[40:41], v[40:41], v[14:15] op_sel_hi:[1,0]
	v_pk_mul_f32 v[38:39], v[38:39], v[14:15] op_sel_hi:[1,0]
	v_pk_mul_f32 v[36:37], v[36:37], v[14:15] op_sel_hi:[1,0]
	v_pk_mul_f32 v[34:35], v[34:35], v[14:15] op_sel_hi:[1,0]
	v_pk_mul_f32 v[32:33], v[32:33], v[14:15] op_sel_hi:[1,0]
	v_pk_mul_f32 v[30:31], v[30:31], v[14:15] op_sel_hi:[1,0]
	v_pk_mul_f32 v[28:29], v[28:29], v[14:15] op_sel_hi:[1,0]
	v_pk_mul_f32 v[26:27], v[26:27], v[14:15] op_sel_hi:[1,0]
	v_pk_mul_f32 v[24:25], v[24:25], v[14:15] op_sel_hi:[1,0]
	v_pk_mul_f32 v[22:23], v[22:23], v[14:15] op_sel_hi:[1,0]
	v_pk_mul_f32 v[20:21], v[20:21], v[14:15] op_sel_hi:[1,0]
	v_pk_mul_f32 v[18:19], v[18:19], v[14:15] op_sel_hi:[1,0]
	v_pk_mul_f32 v[16:17], v[16:17], v[14:15] op_sel_hi:[1,0]
	v_mul_f32_e32 v0, v0, v14
; #define MFMA(a, b, c) __builtin_amdgcn_mfma_f32_32x32x16_bf16((a), (b), (c), 0, 0, 0)
; template <int DK>
; DI void attn_item2(const u16* __restrict__ Q, int ldq, const u16* __restrict__ K, int ldk, const u16* __restrict__ Vt, int nTiles,
;                    u16* __restrict__ Gp, const u16* __restrict__ Zp, char* smem, int tid) {
;     ...
;       for (int ks = 0; ks < KS; ks++) {
;         bf16x8 a = *(const bf16x8*)&Ks[buf][kb * 32 + r][ks * 16 + h * 8];
;         s0 = MFMA(a, qf[0][ks], s0);
;         s1 = MFMA(a, qf[1][ks], s1);
;       }
;       bf16x8 pf0[2], pf1[2];
;     ...
;       SOFTMAX_STEP(s0, m_run0, l_run0, o[0], pf0)
;       SOFTMAX_STEP(s1, m_run1, l_run1, o[1], pf1)
;     ...
; #pragma unroll
;       for (int db = 0; db < 2; db++)
; #pragma unroll
;         for (int sx = 0; sx < 2; sx++) {
;           const u16* vp = &Vs[buf][db * 32 + r][32 * kb + 16 * sx + 4 * h];
;           uint2 lo = *(const uint2*)vp, hi = *(const uint2*)(vp + 8);
;           uint4 u; u.x = lo.x; u.y = lo.y; u.z = hi.x; u.w = hi.y;
;           const bf16x8 a = __builtin_bit_cast(bf16x8, u);
;           o[0][db] = MFMA(a, pf0[sx], o[0][db]);
;           o[1][db] = MFMA(a, pf1[sx], o[1][db]);
;         }
.LBB0_866:
	v_sub_f32_e32 v14, v96, v191
	v_exp_f32_e32 v14, v14
	v_sub_f32_e32 v96, v97, v191
	v_exp_f32_e32 v96, v96
	v_sub_f32_e32 v97, v98, v191
	v_exp_f32_e32 v97, v97
	v_sub_f32_e32 v98, v99, v191
	v_exp_f32_e32 v98, v98
	v_sub_f32_e32 v99, v100, v191
	v_add_f32_e32 v15, 0, v14
	v_exp_f32_e32 v99, v99
	v_sub_f32_e32 v100, v101, v191
	v_add_f32_e32 v15, v96, v15
	v_exp_f32_e32 v231, v100
	v_sub_f32_e32 v100, v102, v191
	v_add_f32_e32 v15, v97, v15
	v_exp_f32_e32 v232, v100
	v_sub_f32_e32 v100, v103, v191
	v_add_f32_e32 v15, v98, v15
	v_exp_f32_e32 v103, v100
	v_sub_f32_e32 v100, v104, v191
	v_add_f32_e32 v15, v99, v15
	v_exp_f32_e32 v104, v100
	v_sub_f32_e32 v100, v105, v191
	v_add_f32_e32 v15, v231, v15
	v_exp_f32_e32 v105, v100
	v_sub_f32_e32 v100, v106, v191
	v_add_f32_e32 v15, v232, v15
	v_exp_f32_e32 v106, v100
	v_sub_f32_e32 v100, v107, v191
	v_add_f32_e32 v15, v103, v15
	v_exp_f32_e32 v107, v100
	v_sub_f32_e32 v100, v108, v191
	v_add_f32_e32 v15, v104, v15
	v_exp_f32_e32 v108, v100
	v_sub_f32_e32 v100, v109, v191
	v_add_f32_e32 v15, v105, v15
	v_exp_f32_e32 v109, v100
	v_sub_f32_e32 v100, v110, v191
	v_add_f32_e32 v15, v106, v15
	v_exp_f32_e32 v110, v100
	v_sub_f32_e32 v100, v111, v191
	v_add_f32_e32 v15, v107, v15
	v_exp_f32_e32 v111, v100
	v_add_f32_e32 v15, v108, v15
	v_add_f32_e32 v15, v109, v15
	v_add_f32_e32 v15, v110, v15
	v_add_f32_e32 v15, v111, v15
	v_add_f32_e32 v229, v229, v15
	v_sub_f32_e32 v15, v80, v189
	v_cvt_pk_bf16_f32 v102, v99, v231
	v_exp_f32_e32 v231, v15
	v_sub_f32_e32 v15, v81, v189
	v_cvt_pk_bf16_f32 v103, v232, v103
	v_exp_f32_e32 v232, v15
	v_sub_f32_e32 v15, v82, v189
	v_exp_f32_e32 v233, v15
	v_sub_f32_e32 v15, v83, v189
	v_exp_f32_e32 v234, v15
	v_sub_f32_e32 v15, v84, v189
	v_exp_f32_e32 v235, v15
	v_sub_f32_e32 v15, v85, v189
	v_exp_f32_e32 v236, v15
	v_sub_f32_e32 v15, v86, v189
	v_exp_f32_e32 v237, v15
	v_sub_f32_e32 v15, v87, v189
	v_exp_f32_e32 v238, v15
	v_sub_f32_e32 v15, v88, v189
	v_exp_f32_e32 v239, v15
	v_sub_f32_e32 v15, v89, v189
	v_exp_f32_e32 v240, v15
	v_sub_f32_e32 v15, v90, v189
	v_exp_f32_e32 v241, v15
	v_sub_f32_e32 v15, v91, v189
	v_exp_f32_e32 v242, v15
	v_sub_f32_e32 v15, v92, v189
	v_exp_f32_e32 v243, v15
	v_sub_f32_e32 v15, v93, v189
	s_mul_i32 s8, s3, 0x2200
	v_exp_f32_e32 v244, v15
	v_sub_f32_e32 v15, v94, v189
	v_cvt_pk_bf16_f32 v100, v14, v96
	v_add_u32_e32 v14, s8, v226
	v_exp_f32_e32 v245, v15
	v_sub_f32_e32 v15, v95, v189
	v_exp_f32_e32 v246, v15
	v_add_u32_e32 v15, 0x4800, v14
	ds_read2_b64 v[88:91], v15 offset1:2
	ds_read2_b64 v[92:95], v15 offset0:4 offset1:6
	v_cvt_pk_bf16_f32 v101, v97, v98
	v_cvt_pk_bf16_f32 v84, v231, v232
	v_cvt_pk_bf16_f32 v85, v233, v234
	v_cvt_pk_bf16_f32 v86, v235, v236
	v_cvt_pk_bf16_f32 v87, v237, v238
	v_add_u32_e32 v14, 0x5800, v14
	s_waitcnt lgkmcnt(1)
	v_mfma_f32_32x32x16_bf16 v[64:79], v[88:91], v[100:103], v[64:79]
	v_cvt_pk_bf16_f32 v80, v239, v240
	v_cvt_pk_bf16_f32 v81, v241, v242
	v_cvt_pk_bf16_f32 v82, v243, v244
	v_cvt_pk_bf16_f32 v83, v245, v246
	v_cvt_pk_bf16_f32 v96, v104, v105
	v_cvt_pk_bf16_f32 v97, v106, v107
	v_cvt_pk_bf16_f32 v98, v108, v109
	v_mfma_f32_32x32x16_bf16 v[32:47], v[88:91], v[84:87], v[32:47]
	ds_read2_b64 v[88:91], v14 offset0:32 offset1:34
	v_cvt_pk_bf16_f32 v99, v110, v111
	s_waitcnt lgkmcnt(0)
	v_mfma_f32_32x32x16_bf16 v[16:31], v[88:91], v[84:87], v[16:31]
	ds_read2_b64 v[84:87], v14 offset0:36 offset1:38
	v_mfma_f32_32x32x16_bf16 v[48:63], v[88:91], v[100:103], v[48:63]
	v_mfma_f32_32x32x16_bf16 v[32:47], v[92:95], v[80:83], v[32:47]
	s_waitcnt lgkmcnt(0)
	v_mfma_f32_32x32x16_bf16 v[16:31], v[84:87], v[80:83], v[16:31]
	ds_read_b128 v[80:83], v230 offset:4608
	ds_read_b128 v[248:251], v230 offset:4640
	v_mfma_f32_32x32x16_bf16 v[64:79], v[92:95], v[96:99], v[64:79]
	v_mfma_f32_32x32x16_bf16 v[48:63], v[84:87], v[96:99], v[48:63]
	s_waitcnt lgkmcnt(1)
	v_mfma_f32_32x32x16_bf16 v[96:111], v[80:83], v[132:135], 0
	v_mfma_f32_32x32x16_bf16 v[80:95], v[80:83], v[140:143], 0
	s_waitcnt lgkmcnt(0)
	v_mfma_f32_32x32x16_bf16 v[96:111], v[248:251], v[124:127], v[96:111]
	v_mfma_f32_32x32x16_bf16 v[80:95], v[248:251], v[136:139], v[80:95]
	ds_read_b128 v[248:251], v230 offset:4672
	s_waitcnt lgkmcnt(0)
	v_mfma_f32_32x32x16_bf16 v[96:111], v[248:251], v[120:123], v[96:111]
	v_mfma_f32_32x32x16_bf16 v[80:95], v[248:251], v[128:131], v[80:95]
	ds_read_b128 v[248:251], v230 offset:4704
	s_waitcnt lgkmcnt(0)
	v_mfma_f32_32x32x16_bf16 v[96:111], v[248:251], v[112:115], v[96:111]
	v_mfma_f32_32x32x16_bf16 v[80:95], v[248:251], v[116:119], v[80:95]
	s_nop 10
	v_max3_f32 v230, v96, v97, v98
	v_max3_f32 v247, v99, v100, v101
	v_max3_f32 v248, v102, v103, v104
	v_max3_f32 v249, v105, v106, v107
	v_max3_f32 v250, v108, v109, v110
	v_max3_f32 v230, v230, v247, v248
	v_max3_f32 v249, v249, v250, v111
	v_max_f32_e32 v230, v230, v249
	v_mov_b32_e32 v247, v230
	s_nop 1
	v_permlane32_swap_b32_e32 v230, v247
	v_max_f32_e32 v247, v247, v247
	v_max_f32_e32 v230, v230, v230
	v_max_f32_e32 v230, v230, v247
	v_add_f32_e32 v247, 4.0, v191
	v_cmp_gt_f32_e32 vcc, v230, v247
	s_cbranch_vccz .LBB0_868
	v_max_f32_e32 v230, v230, v230
	v_max_f32_e32 v247, v191, v191
	v_max_f32_e32 v247, v247, v230
	v_sub_f32_e32 v191, v191, v247
	v_exp_f32_e32 v230, v191
	v_mov_b32_e32 v191, v247
	v_pk_mul_f32 v[78:79], v[78:79], v[230:231] op_sel_hi:[1,0]
	v_pk_mul_f32 v[76:77], v[76:77], v[230:231] op_sel_hi:[1,0]
	v_pk_mul_f32 v[74:75], v[74:75], v[230:231] op_sel_hi:[1,0]
	v_pk_mul_f32 v[72:73], v[72:73], v[230:231] op_sel_hi:[1,0]
	v_pk_mul_f32 v[70:71], v[70:71], v[230:231] op_sel_hi:[1,0]
	v_pk_mul_f32 v[68:69], v[68:69], v[230:231] op_sel_hi:[1,0]
	v_pk_mul_f32 v[66:67], v[66:67], v[230:231] op_sel_hi:[1,0]
	v_pk_mul_f32 v[64:65], v[64:65], v[230:231] op_sel_hi:[1,0]
	v_pk_mul_f32 v[62:63], v[62:63], v[230:231] op_sel_hi:[1,0]
	v_pk_mul_f32 v[60:61], v[60:61], v[230:231] op_sel_hi:[1,0]
	v_pk_mul_f32 v[58:59], v[58:59], v[230:231] op_sel_hi:[1,0]
	v_pk_mul_f32 v[56:57], v[56:57], v[230:231] op_sel_hi:[1,0]
	v_pk_mul_f32 v[54:55], v[54:55], v[230:231] op_sel_hi:[1,0]
	v_pk_mul_f32 v[52:53], v[52:53], v[230:231] op_sel_hi:[1,0]
	v_pk_mul_f32 v[50:51], v[50:51], v[230:231] op_sel_hi:[1,0]
	v_pk_mul_f32 v[48:49], v[48:49], v[230:231] op_sel_hi:[1,0]
	v_mul_f32_e32 v229, v229, v230
; #define MFMA(a, b, c) __builtin_amdgcn_mfma_f32_32x32x16_bf16((a), (b), (c), 0, 0, 0)
; #define GLOAD(t) { const int pos0_ = TILE_POS(t); \
;     rk0 = *(const uint4*)(K + (size_t)(pos0_ + kr0) * ldk + kc0); rk1 = *(const uint4*)(K + (size_t)(pos0_ + kr1) * ldk + kc1); \
;     if (NKC == 3) rk2 = *(const uint4*)(K + (size_t)(pos0_ + kr2) * ldk + kc2); \
;     rv0 = *(const uint4*)(Vt + (size_t)vd0 * SEQA + pos0_ + vk0); rv1 = *(const uint4*)(Vt + (size_t)(vd0 + 32) * SEQA + pos0_ + vk0); }
; #define GLOAD(t) { const int pos0_ = (t) * 64; \
;     rk0 = *(const uint4*)(K + (size_t)(pos0_ + kr0) * ldk + kc0); rk1 = *(const uint4*)(K + (size_t)(pos0_ + kr1) * ldk + kc1); \
;     if (NKC == 3) rk2 = *(const uint4*)(K + (size_t)(pos0_ + kr2) * ldk + kc2); \
;     rv0 = *(const uint4*)(Vt + (size_t)vd0 * SEQA + pos0_ + vk0); rv1 = *(const uint4*)(Vt + (size_t)(vd0 + 32) * SEQA + pos0_ + vk0); }
; template <int DK>
; DI void attn_item2(const u16* __restrict__ Q, int ldq, const u16* __restrict__ K, int ldk, const u16* __restrict__ Vt, int nTiles,
;                    u16* __restrict__ Gp, const u16* __restrict__ Zp, char* smem, int tid) {
;     ...
;   for (int t = 0; t < nTiles; t++) {
;     const int buf = t & 1;
;     if (t + 1 < nTiles) GLOAD(t + 1);
; #pragma unroll
;     for (int kb = 0; kb < 2; kb++) {
;       f32x16 s0, s1;
; #pragma unroll
;       for (int i = 0; i < 16; i++) { s0[i] = 0.f; s1[i] = 0.f; }
; #pragma unroll
;       for (int ks = 0; ks < KS; ks++) {
;         bf16x8 a = *(const bf16x8*)&Ks[buf][kb * 32 + r][ks * 16 + h * 8];
;         s0 = MFMA(a, qf[0][ks], s0);
;         s1 = MFMA(a, qf[1][ks], s1);
;       }
;       bf16x8 pf0[2], pf1[2];
;     ...
;       SOFTMAX_STEP(s0, m_run0, l_run0, o[0], pf0)
;       SOFTMAX_STEP(s1, m_run1, l_run1, o[1], pf1)
.LBB0_868:
	v_add_f32_e32 v230, 0, v231
	v_add_f32_e32 v230, v232, v230
	v_add_f32_e32 v230, v233, v230
	v_add_f32_e32 v230, v234, v230
	v_add_f32_e32 v230, v235, v230
	v_add_f32_e32 v230, v236, v230
	v_add_f32_e32 v230, v237, v230
	v_add_f32_e32 v230, v238, v230
	v_add_f32_e32 v230, v239, v230
	v_add_f32_e32 v230, v240, v230
	v_add_f32_e32 v230, v241, v230
	v_add_f32_e32 v230, v242, v230
	v_add_f32_e32 v230, v243, v230
	v_add_f32_e32 v230, v244, v230
	v_add_f32_e32 v230, v245, v230
	v_add_f32_e32 v230, v246, v230
	v_add_f32_e32 v0, v0, v230
	v_max3_f32 v230, v80, v81, v82
	v_max3_f32 v231, v83, v84, v85
	v_max3_f32 v232, v86, v87, v88
	v_max3_f32 v233, v89, v90, v91
	v_max3_f32 v234, v92, v93, v94
	v_max3_f32 v230, v230, v231, v232
	v_max3_f32 v233, v233, v234, v95
	v_max_f32_e32 v230, v230, v233
	v_mov_b32_e32 v231, v230
	s_nop 1
	v_permlane32_swap_b32_e32 v230, v231
	v_max_f32_e32 v231, v231, v231
	v_max_f32_e32 v230, v230, v230
	v_max_f32_e32 v230, v230, v231
	v_add_f32_e32 v231, 4.0, v189
	v_cmp_gt_f32_e32 vcc, v230, v231
	s_cbranch_vccz .LBB0_861
	v_max_f32_e32 v230, v230, v230
	v_max_f32_e32 v231, v189, v189
	v_max_f32_e32 v231, v231, v230
	v_sub_f32_e32 v189, v189, v231
	v_exp_f32_e32 v230, v189
	v_mov_b32_e32 v189, v231
	v_pk_mul_f32 v[46:47], v[46:47], v[230:231] op_sel_hi:[1,0]
	v_pk_mul_f32 v[44:45], v[44:45], v[230:231] op_sel_hi:[1,0]
	v_pk_mul_f32 v[42:43], v[42:43], v[230:231] op_sel_hi:[1,0]
	v_pk_mul_f32 v[40:41], v[40:41], v[230:231] op_sel_hi:[1,0]
	v_pk_mul_f32 v[38:39], v[38:39], v[230:231] op_sel_hi:[1,0]
	v_pk_mul_f32 v[36:37], v[36:37], v[230:231] op_sel_hi:[1,0]
	v_pk_mul_f32 v[34:35], v[34:35], v[230:231] op_sel_hi:[1,0]
	v_pk_mul_f32 v[32:33], v[32:33], v[230:231] op_sel_hi:[1,0]
	v_pk_mul_f32 v[30:31], v[30:31], v[230:231] op_sel_hi:[1,0]
	v_pk_mul_f32 v[28:29], v[28:29], v[230:231] op_sel_hi:[1,0]
	v_pk_mul_f32 v[26:27], v[26:27], v[230:231] op_sel_hi:[1,0]
	v_pk_mul_f32 v[24:25], v[24:25], v[230:231] op_sel_hi:[1,0]
	v_pk_mul_f32 v[22:23], v[22:23], v[230:231] op_sel_hi:[1,0]
	v_pk_mul_f32 v[20:21], v[20:21], v[230:231] op_sel_hi:[1,0]
	v_pk_mul_f32 v[18:19], v[18:19], v[230:231] op_sel_hi:[1,0]
	v_pk_mul_f32 v[16:17], v[16:17], v[230:231] op_sel_hi:[1,0]
	v_mul_f32_e32 v0, v0, v230
	s_branch .LBB0_861
.LBB0_870:
	s_or_b64 exec, exec, s[6:7]
	v_and_b32_e32 v10, 1, v193
	v_mad_u32_u24 v14, v10, s28, v225
	ds_read_b128 v[2:5], v14
	ds_read_b128 v[6:9], v14 offset:32
	s_waitcnt lgkmcnt(1)
	v_mfma_f32_32x32x16_bf16 v[96:111], v[2:5], v[132:135], 0
	v_mfma_f32_32x32x16_bf16 v[80:95], v[2:5], v[140:143], 0
	ds_read_b128 v[2:5], v14 offset:64
	s_waitcnt lgkmcnt(1)
	v_mfma_f32_32x32x16_bf16 v[96:111], v[6:9], v[124:127], v[96:111]
	v_mfma_f32_32x32x16_bf16 v[80:95], v[6:9], v[136:139], v[80:95]
	s_waitcnt lgkmcnt(0)
	v_mfma_f32_32x32x16_bf16 v[96:111], v[2:5], v[120:123], v[96:111]
	v_mfma_f32_32x32x16_bf16 v[80:95], v[2:5], v[128:131], v[80:95]
	ds_read_b128 v[2:5], v14 offset:96
	s_waitcnt lgkmcnt(0)
	v_mfma_f32_32x32x16_bf16 v[96:111], v[2:5], v[112:115], v[96:111]
	v_mfma_f32_32x32x16_bf16 v[80:95], v[2:5], v[116:119], v[80:95]
	s_nop 10
	v_max3_f32 v2, v96, v97, v98
	v_max3_f32 v3, v99, v100, v101
	v_max3_f32 v4, v102, v103, v104
	v_max3_f32 v5, v105, v106, v107
	v_max3_f32 v6, v108, v109, v110
	v_max3_f32 v2, v2, v3, v4
	v_max3_f32 v5, v5, v6, v111
	v_max_f32_e32 v2, v2, v5
	v_mov_b32_e32 v3, v2
	s_nop 1
	v_permlane32_swap_b32_e32 v2, v3
	v_max_f32_e32 v3, v3, v3
	v_max_f32_e32 v2, v2, v2
	v_max_f32_e32 v2, v2, v3
	v_add_f32_e32 v3, 4.0, v191
	v_cmp_gt_f32_e32 vcc, v2, v3
	s_cbranch_vccz .LBB0_872
	v_max_f32_e32 v2, v2, v2
	v_max_f32_e32 v3, v191, v191
	v_max_f32_e32 v3, v3, v2
	v_sub_f32_e32 v2, v191, v3
	v_exp_f32_e32 v2, v2
	v_mov_b32_e32 v191, v3
	v_pk_mul_f32 v[78:79], v[78:79], v[2:3] op_sel_hi:[1,0]
	v_pk_mul_f32 v[76:77], v[76:77], v[2:3] op_sel_hi:[1,0]
	v_pk_mul_f32 v[74:75], v[74:75], v[2:3] op_sel_hi:[1,0]
	v_pk_mul_f32 v[72:73], v[72:73], v[2:3] op_sel_hi:[1,0]
	v_pk_mul_f32 v[70:71], v[70:71], v[2:3] op_sel_hi:[1,0]
	v_pk_mul_f32 v[68:69], v[68:69], v[2:3] op_sel_hi:[1,0]
	v_pk_mul_f32 v[66:67], v[66:67], v[2:3] op_sel_hi:[1,0]
	v_pk_mul_f32 v[64:65], v[64:65], v[2:3] op_sel_hi:[1,0]
	v_pk_mul_f32 v[62:63], v[62:63], v[2:3] op_sel_hi:[1,0]
	v_pk_mul_f32 v[60:61], v[60:61], v[2:3] op_sel_hi:[1,0]
	v_pk_mul_f32 v[58:59], v[58:59], v[2:3] op_sel_hi:[1,0]
	v_pk_mul_f32 v[56:57], v[56:57], v[2:3] op_sel_hi:[1,0]
	v_pk_mul_f32 v[54:55], v[54:55], v[2:3] op_sel_hi:[1,0]
	v_pk_mul_f32 v[52:53], v[52:53], v[2:3] op_sel_hi:[1,0]
	v_pk_mul_f32 v[50:51], v[50:51], v[2:3] op_sel_hi:[1,0]
	v_pk_mul_f32 v[48:49], v[48:49], v[2:3] op_sel_hi:[1,0]
	v_mul_f32_e32 v229, v229, v2
.LBB0_872:
	v_max3_f32 v2, v80, v81, v82
	v_max3_f32 v3, v83, v84, v85
	v_max3_f32 v4, v86, v87, v88
	v_max3_f32 v5, v89, v90, v91
	v_max3_f32 v6, v92, v93, v94
	v_max3_f32 v2, v2, v3, v4
	v_max3_f32 v5, v5, v6, v95
	v_max_f32_e32 v2, v2, v5
	v_mov_b32_e32 v3, v2
	s_nop 1
	v_permlane32_swap_b32_e32 v2, v3
	v_max_f32_e32 v3, v3, v3
	v_max_f32_e32 v2, v2, v2
	v_max_f32_e32 v2, v2, v3
	v_add_f32_e32 v3, 4.0, v189
	v_cmp_gt_f32_e32 vcc, v2, v3
	s_cbranch_vccz .LBB0_874
	v_max_f32_e32 v2, v2, v2
	v_max_f32_e32 v3, v189, v189
	v_max_f32_e32 v3, v3, v2
	v_sub_f32_e32 v2, v189, v3
	v_exp_f32_e32 v2, v2
	v_mov_b32_e32 v189, v3
	v_pk_mul_f32 v[46:47], v[46:47], v[2:3] op_sel_hi:[1,0]
	v_pk_mul_f32 v[44:45], v[44:45], v[2:3] op_sel_hi:[1,0]
	v_pk_mul_f32 v[42:43], v[42:43], v[2:3] op_sel_hi:[1,0]
	v_pk_mul_f32 v[40:41], v[40:41], v[2:3] op_sel_hi:[1,0]
	v_pk_mul_f32 v[38:39], v[38:39], v[2:3] op_sel_hi:[1,0]
	v_pk_mul_f32 v[36:37], v[36:37], v[2:3] op_sel_hi:[1,0]
	v_pk_mul_f32 v[34:35], v[34:35], v[2:3] op_sel_hi:[1,0]
	v_pk_mul_f32 v[32:33], v[32:33], v[2:3] op_sel_hi:[1,0]
	v_pk_mul_f32 v[30:31], v[30:31], v[2:3] op_sel_hi:[1,0]
	v_pk_mul_f32 v[28:29], v[28:29], v[2:3] op_sel_hi:[1,0]
	v_pk_mul_f32 v[26:27], v[26:27], v[2:3] op_sel_hi:[1,0]
	v_pk_mul_f32 v[24:25], v[24:25], v[2:3] op_sel_hi:[1,0]
	v_pk_mul_f32 v[22:23], v[22:23], v[2:3] op_sel_hi:[1,0]
	v_pk_mul_f32 v[20:21], v[20:21], v[2:3] op_sel_hi:[1,0]
	v_pk_mul_f32 v[18:19], v[18:19], v[2:3] op_sel_hi:[1,0]
	v_pk_mul_f32 v[16:17], v[16:17], v[2:3] op_sel_hi:[1,0]
	v_mul_f32_e32 v0, v0, v2
; #define MFMA(a, b, c) __builtin_amdgcn_mfma_f32_32x32x16_bf16((a), (b), (c), 0, 0, 0)
; template <int DK>
; DI void attn_item2(const u16* __restrict__ Q, int ldq, const u16* __restrict__ K, int ldk, const u16* __restrict__ Vt, int nTiles,
;                    u16* __restrict__ Gp, const u16* __restrict__ Zp, char* smem, int tid) {
;     ...
;       for (int ks = 0; ks < KS; ks++) {
;         bf16x8 a = *(const bf16x8*)&Ks[buf][kb * 32 + r][ks * 16 + h * 8];
;         s0 = MFMA(a, qf[0][ks], s0);
;         s1 = MFMA(a, qf[1][ks], s1);
;       }
;       bf16x8 pf0[2], pf1[2];
;     ...
;       SOFTMAX_STEP(s0, m_run0, l_run0, o[0], pf0)
;       SOFTMAX_STEP(s1, m_run1, l_run1, o[1], pf1)
;     ...
; #pragma unroll
;       for (int db = 0; db < 2; db++)
; #pragma unroll
;         for (int sx = 0; sx < 2; sx++) {
;           const u16* vp = &Vs[buf][db * 32 + r][32 * kb + 16 * sx + 4 * h];
;           uint2 lo = *(const uint2*)vp, hi = *(const uint2*)(vp + 8);
;           uint4 u; u.x = lo.x; u.y = lo.y; u.z = hi.x; u.w = hi.y;
;           const bf16x8 a = __builtin_bit_cast(bf16x8, u);
;           o[0][db] = MFMA(a, pf0[sx], o[0][db]);
;           o[1][db] = MFMA(a, pf1[sx], o[1][db]);
;         }
.LBB0_874:
	v_sub_f32_e32 v2, v96, v191
	v_exp_f32_e32 v2, v2
	v_sub_f32_e32 v4, v97, v191
	v_exp_f32_e32 v4, v4
	v_sub_f32_e32 v5, v98, v191
	v_exp_f32_e32 v5, v5
	v_sub_f32_e32 v6, v99, v191
	v_exp_f32_e32 v7, v6
	v_sub_f32_e32 v6, v100, v191
	v_add_f32_e32 v3, 0, v2
	v_exp_f32_e32 v8, v6
	v_sub_f32_e32 v6, v101, v191
	v_add_f32_e32 v3, v4, v3
	v_exp_f32_e32 v9, v6
	v_sub_f32_e32 v6, v102, v191
	v_add_f32_e32 v3, v5, v3
	v_exp_f32_e32 v11, v6
	v_sub_f32_e32 v6, v103, v191
	v_add_f32_e32 v3, v7, v3
	v_exp_f32_e32 v12, v6
	v_sub_f32_e32 v6, v104, v191
	v_add_f32_e32 v3, v8, v3
	v_exp_f32_e32 v13, v6
	v_sub_f32_e32 v6, v105, v191
	v_add_f32_e32 v3, v9, v3
	v_exp_f32_e32 v15, v6
	v_sub_f32_e32 v6, v106, v191
	v_add_f32_e32 v3, v11, v3
	v_exp_f32_e32 v96, v6
	v_sub_f32_e32 v6, v107, v191
	v_add_f32_e32 v3, v12, v3
	v_exp_f32_e32 v97, v6
	v_sub_f32_e32 v6, v108, v191
	v_add_f32_e32 v3, v13, v3
	v_exp_f32_e32 v98, v6
	v_sub_f32_e32 v6, v109, v191
	v_add_f32_e32 v3, v15, v3
	v_exp_f32_e32 v99, v6
	v_sub_f32_e32 v6, v110, v191
	v_add_f32_e32 v3, v96, v3
	v_exp_f32_e32 v100, v6
	v_sub_f32_e32 v6, v111, v191
	v_add_f32_e32 v3, v97, v3
	v_exp_f32_e32 v101, v6
	v_add_f32_e32 v3, v98, v3
	v_add_f32_e32 v3, v99, v3
	v_add_f32_e32 v3, v100, v3
	v_add_f32_e32 v102, v101, v3
	v_cvt_pk_bf16_f32 v3, v96, v97
	v_mad_u32_u24 v96, v10, s23, v226
	v_sub_f32_e32 v10, v80, v189
	v_cvt_pk_bf16_f32 v6, v2, v4
	v_cvt_pk_bf16_f32 v2, v13, v15
	v_exp_f32_e32 v15, v10
	v_sub_f32_e32 v10, v81, v189
	v_exp_f32_e32 v147, v10
	v_sub_f32_e32 v10, v82, v189
	v_exp_f32_e32 v193, v10
	v_sub_f32_e32 v10, v83, v189
	v_exp_f32_e32 v198, v10
	v_sub_f32_e32 v10, v84, v189
	v_exp_f32_e32 v199, v10
	v_sub_f32_e32 v10, v85, v189
	v_exp_f32_e32 v200, v10
	v_sub_f32_e32 v10, v86, v189
	v_exp_f32_e32 v201, v10
	v_sub_f32_e32 v10, v87, v189
	v_exp_f32_e32 v202, v10
	v_sub_f32_e32 v10, v88, v189
	v_exp_f32_e32 v203, v10
	v_sub_f32_e32 v10, v89, v189
	v_exp_f32_e32 v204, v10
	v_sub_f32_e32 v10, v90, v189
	v_add_u32_e32 v146, 0x4800, v96
	v_exp_f32_e32 v205, v10
	v_sub_f32_e32 v10, v91, v189
	ds_read2_b64 v[84:87], v146 offset1:2
	ds_read2_b64 v[88:91], v146 offset0:4 offset1:6
	v_cvt_pk_bf16_f32 v7, v5, v7
	v_cvt_pk_bf16_f32 v8, v8, v9
	v_cvt_pk_bf16_f32 v9, v11, v12
	v_cvt_pk_bf16_f32 v80, v15, v147
	v_cvt_pk_bf16_f32 v81, v193, v198
	v_cvt_pk_bf16_f32 v82, v199, v200
	v_cvt_pk_bf16_f32 v83, v201, v202
	v_add_u32_e32 v145, 0x5800, v96
	s_waitcnt lgkmcnt(1)
	v_mfma_f32_32x32x16_bf16 v[64:79], v[84:87], v[6:9], v[64:79]
	v_add_f32_e32 v144, v229, v102
	v_exp_f32_e32 v229, v10
	v_sub_f32_e32 v10, v92, v189
	v_exp_f32_e32 v230, v10
	v_sub_f32_e32 v10, v93, v189
	v_exp_f32_e32 v231, v10
	v_sub_f32_e32 v10, v94, v189
	v_mfma_f32_32x32x16_bf16 v[32:47], v[84:87], v[80:83], v[32:47]
	ds_read2_b64 v[84:87], v145 offset0:32 offset1:34
	v_exp_f32_e32 v232, v10
	v_sub_f32_e32 v10, v95, v189
	v_exp_f32_e32 v233, v10
	v_cvt_pk_bf16_f32 v4, v98, v99
	v_cvt_pk_bf16_f32 v5, v100, v101
	v_cvt_pk_bf16_f32 v10, v203, v204
	s_waitcnt lgkmcnt(0)
	v_mfma_f32_32x32x16_bf16 v[48:63], v[84:87], v[6:9], v[48:63]
	ds_read2_b64 v[6:9], v145 offset0:36 offset1:38
	v_cvt_pk_bf16_f32 v11, v205, v229
	v_cvt_pk_bf16_f32 v12, v230, v231
	v_cvt_pk_bf16_f32 v13, v232, v233
	v_mfma_f32_32x32x16_bf16 v[16:31], v[84:87], v[80:83], v[16:31]
	v_mfma_f32_32x32x16_bf16 v[64:79], v[88:91], v[2:5], v[64:79]
	s_waitcnt lgkmcnt(0)
	v_mfma_f32_32x32x16_bf16 v[48:63], v[6:9], v[2:5], v[48:63]
	v_mfma_f32_32x32x16_bf16 v[16:31], v[6:9], v[10:13], v[16:31]
	ds_read_b128 v[2:5], v14 offset:4608
	ds_read_b128 v[6:9], v14 offset:4640
	v_mfma_f32_32x32x16_bf16 v[32:47], v[88:91], v[10:13], v[32:47]
	s_waitcnt lgkmcnt(1)
	v_mfma_f32_32x32x16_bf16 v[96:111], v[2:5], v[132:135], 0
	v_mfma_f32_32x32x16_bf16 v[80:95], v[2:5], v[140:143], 0
	ds_read_b128 v[2:5], v14 offset:4672
	s_waitcnt lgkmcnt(1)
	v_mfma_f32_32x32x16_bf16 v[96:111], v[6:9], v[124:127], v[96:111]
	v_mfma_f32_32x32x16_bf16 v[80:95], v[6:9], v[136:139], v[80:95]
	s_waitcnt lgkmcnt(0)
	v_mfma_f32_32x32x16_bf16 v[96:111], v[2:5], v[120:123], v[96:111]
	v_mfma_f32_32x32x16_bf16 v[80:95], v[2:5], v[128:131], v[80:95]
	ds_read_b128 v[2:5], v14 offset:4704
	s_waitcnt lgkmcnt(0)
	v_mfma_f32_32x32x16_bf16 v[96:111], v[2:5], v[112:115], v[96:111]
	v_mfma_f32_32x32x16_bf16 v[80:95], v[2:5], v[116:119], v[80:95]
	s_nop 10
	v_max3_f32 v2, v96, v97, v98
	v_max3_f32 v3, v99, v100, v101
	v_max3_f32 v4, v102, v103, v104
	v_max3_f32 v5, v105, v106, v107
	v_max3_f32 v6, v108, v109, v110
	v_max3_f32 v2, v2, v3, v4
	v_max3_f32 v5, v5, v6, v111
	v_max_f32_e32 v2, v2, v5
	v_mov_b32_e32 v3, v2
	s_nop 1
	v_permlane32_swap_b32_e32 v2, v3
	v_max_f32_e32 v3, v3, v3
	v_max_f32_e32 v2, v2, v2
	v_max_f32_e32 v2, v2, v3
	v_add_f32_e32 v3, 4.0, v191
	v_cmp_gt_f32_e32 vcc, v2, v3
	s_cbranch_vccz .LBB0_876
	v_max_f32_e32 v2, v2, v2
	v_max_f32_e32 v3, v191, v191
	v_max_f32_e32 v3, v3, v2
	v_sub_f32_e32 v2, v191, v3
	v_exp_f32_e32 v2, v2
	v_mov_b32_e32 v191, v3
	v_pk_mul_f32 v[78:79], v[78:79], v[2:3] op_sel_hi:[1,0]
	v_pk_mul_f32 v[76:77], v[76:77], v[2:3] op_sel_hi:[1,0]
	v_pk_mul_f32 v[74:75], v[74:75], v[2:3] op_sel_hi:[1,0]
	v_pk_mul_f32 v[72:73], v[72:73], v[2:3] op_sel_hi:[1,0]
	v_pk_mul_f32 v[70:71], v[70:71], v[2:3] op_sel_hi:[1,0]
	v_pk_mul_f32 v[68:69], v[68:69], v[2:3] op_sel_hi:[1,0]
	v_pk_mul_f32 v[66:67], v[66:67], v[2:3] op_sel_hi:[1,0]
	v_pk_mul_f32 v[64:65], v[64:65], v[2:3] op_sel_hi:[1,0]
	v_pk_mul_f32 v[62:63], v[62:63], v[2:3] op_sel_hi:[1,0]
	v_pk_mul_f32 v[60:61], v[60:61], v[2:3] op_sel_hi:[1,0]
	v_pk_mul_f32 v[58:59], v[58:59], v[2:3] op_sel_hi:[1,0]
	v_pk_mul_f32 v[56:57], v[56:57], v[2:3] op_sel_hi:[1,0]
	v_pk_mul_f32 v[54:55], v[54:55], v[2:3] op_sel_hi:[1,0]
	v_pk_mul_f32 v[52:53], v[52:53], v[2:3] op_sel_hi:[1,0]
	v_pk_mul_f32 v[50:51], v[50:51], v[2:3] op_sel_hi:[1,0]
	v_pk_mul_f32 v[48:49], v[48:49], v[2:3] op_sel_hi:[1,0]
	v_mul_f32_e32 v144, v144, v2
.LBB0_876:
	v_add_f32_e32 v2, 0, v15
	v_add_f32_e32 v2, v147, v2
	v_add_f32_e32 v2, v193, v2
	v_add_f32_e32 v2, v198, v2
	v_add_f32_e32 v2, v199, v2
	v_add_f32_e32 v2, v200, v2
	v_add_f32_e32 v2, v201, v2
	v_add_f32_e32 v2, v202, v2
	v_add_f32_e32 v2, v203, v2
	v_add_f32_e32 v2, v204, v2
	v_add_f32_e32 v2, v205, v2
	v_add_f32_e32 v2, v229, v2
	v_add_f32_e32 v2, v230, v2
	v_add_f32_e32 v2, v231, v2
	v_add_f32_e32 v2, v232, v2
	v_add_f32_e32 v2, v233, v2
	v_add_f32_e32 v112, v0, v2
	v_max3_f32 v0, v80, v81, v82
	v_max3_f32 v2, v83, v84, v85
	v_max3_f32 v3, v86, v87, v88
	v_max3_f32 v4, v89, v90, v91
	v_max3_f32 v5, v92, v93, v94
	v_max3_f32 v0, v0, v2, v3
	v_max3_f32 v4, v4, v5, v95
	v_max_f32_e32 v0, v0, v4
	v_mov_b32_e32 v2, v0
	s_nop 1
	v_permlane32_swap_b32_e32 v0, v2
	v_max_f32_e32 v2, v2, v2
	v_max_f32_e32 v0, v0, v0
	v_max_f32_e32 v0, v0, v2
	v_add_f32_e32 v2, 4.0, v189
	v_cmp_gt_f32_e32 vcc, v0, v2
	s_cbranch_vccz .LBB0_878
	v_max_f32_e32 v0, v0, v0
	v_max_f32_e32 v2, v189, v189
	v_max_f32_e32 v2, v2, v0
	v_sub_f32_e32 v0, v189, v2
	v_exp_f32_e32 v0, v0
	v_mov_b32_e32 v189, v2
	v_pk_mul_f32 v[46:47], v[46:47], v[0:1] op_sel_hi:[1,0]
	v_pk_mul_f32 v[44:45], v[44:45], v[0:1] op_sel_hi:[1,0]
	v_pk_mul_f32 v[42:43], v[42:43], v[0:1] op_sel_hi:[1,0]
	v_pk_mul_f32 v[40:41], v[40:41], v[0:1] op_sel_hi:[1,0]
	v_pk_mul_f32 v[38:39], v[38:39], v[0:1] op_sel_hi:[1,0]
	v_pk_mul_f32 v[36:37], v[36:37], v[0:1] op_sel_hi:[1,0]
	v_pk_mul_f32 v[34:35], v[34:35], v[0:1] op_sel_hi:[1,0]
	v_pk_mul_f32 v[32:33], v[32:33], v[0:1] op_sel_hi:[1,0]
	v_pk_mul_f32 v[30:31], v[30:31], v[0:1] op_sel_hi:[1,0]
	v_pk_mul_f32 v[28:29], v[28:29], v[0:1] op_sel_hi:[1,0]
	v_pk_mul_f32 v[26:27], v[26:27], v[0:1] op_sel_hi:[1,0]
	v_pk_mul_f32 v[24:25], v[24:25], v[0:1] op_sel_hi:[1,0]
	v_pk_mul_f32 v[22:23], v[22:23], v[0:1] op_sel_hi:[1,0]
	v_pk_mul_f32 v[20:21], v[20:21], v[0:1] op_sel_hi:[1,0]
	v_pk_mul_f32 v[18:19], v[18:19], v[0:1] op_sel_hi:[1,0]
	v_pk_mul_f32 v[16:17], v[16:17], v[0:1] op_sel_hi:[1,0]
	v_mul_f32_e32 v112, v112, v0

; #define GLOAD(t) { const int pos0_ = TILE_POS(t); \
;     rk0 = *(const uint4*)(K + (size_t)(pos0_ + kr0) * ldk + kc0); rk1 = *(const uint4*)(K + (size_t)(pos0_ + kr1) * ldk + kc1); \
;     if (NKC == 3) rk2 = *(const uint4*)(K + (size_t)(pos0_ + kr2) * ldk + kc2); \
;     rv0 = *(const uint4*)(Vt + (size_t)vd0 * SEQA + pos0_ + vk0); rv1 = *(const uint4*)(Vt + (size_t)(vd0 + 32) * SEQA + pos0_ + vk0); }
; #define LSTORE(bf) { *(uint4*)&Ks[bf][kr0][kc0] = rk0; *(uint4*)&Ks[bf][kr1][kc1] = rk1; if (NKC == 3) *(uint4*)&Ks[bf][kr2][kc2] = rk2; \
;     *(uint2*)&Vs[bf][vd0][vk0] = make_uint2(rv0.x, rv0.y); *(uint2*)&Vs[bf][vd0][vk0 + 4] = make_uint2(rv0.z, rv0.w); \
;     *(uint2*)&Vs[bf][vd0 + 32][vk0] = make_uint2(rv1.x, rv1.y); *(uint2*)&Vs[bf][vd0 + 32][vk0 + 4] = make_uint2(rv1.z, rv1.w); }
; #define GLOAD(t) { const int pos0_ = (t) * 64; \
;     rk0 = *(const uint4*)(K + (size_t)(pos0_ + kr0) * ldk + kc0); rk1 = *(const uint4*)(K + (size_t)(pos0_ + kr1) * ldk + kc1); \
;     if (NKC == 3) rk2 = *(const uint4*)(K + (size_t)(pos0_ + kr2) * ldk + kc2); \
;     rv0 = *(const uint4*)(Vt + (size_t)vd0 * SEQA + pos0_ + vk0); rv1 = *(const uint4*)(Vt + (size_t)(vd0 + 32) * SEQA + pos0_ + vk0); }
; template <int DK, bool NA> ...
;     ...
;   __syncthreads();
;   if (NA) { for (int i = tid; i < 465; i += 256) biasL[i] = relb_h[i] * LOG2E; }
;   bf16x8 qf[KS];
;   {
;     const u16* qrow = Q + (size_t)(w * 32 + r) * ldq + h * 8;
; #pragma unroll
;     for (int ks = 0; ks < KS; ks++) qf[ks] = *(const bf16x8*)(qrow + ks * 16);
;   }
;   const int iw = 2 * pr + (w >> 1), rsw = clampi(iw - 4, 0, 56), jq = 32 * (w & 1) + r, cs = clampi(jq - 8, 0, 48);
;   f32x16 o[2];
; #pragma unroll
;   for (int i = 0; i < 16; i++) { o[0][i] = 0.f; o[1][i] = 0.f; }
;   float m_run = -1e30f, l_run = 0.f;
;   uint4 rk0, rk1, rk2, rv0, rv1;
;   rk2 = make_uint4(0, 0, 0, 0);
;   const int kr0 = tid / KCH, kc0 = (tid % KCH) * 8, kr1 = (tid + 256) / KCH, kc1 = ((tid + 256) % KCH) * 8, kr2 = (tid + 512) / KCH, kc2 = ((tid + 512) % KCH) * 8;
;   const int vd0 = tid >> 3, vk0 = (tid & 7) * 8;
;     ...
;   GLOAD(0); LSTORE(0);
;   __syncthreads();
.LBB0_889:
	v_cmp_gt_i32_e32 vcc, s11, v0
	s_and_saveexec_b64 s[2:3], vcc
	s_xor_b64 s[2:3], exec, s[2:3]
	v_ashrrev_i32_e32 v2, 7, v0
	s_or_saveexec_b64 s[6:7], s[2:3]
	v_mov_b64_e32 v[4:5], 0x100
	v_mov_b32_e32 v5, 0x42
	v_mov_b32_e32 v3, 31
	v_mov_b32_e32 v6, 5
	s_mov_b64 s[12:13], 0x3000
	s_xor_b64 exec, exec, s[6:7]
	v_add_u32_e32 v2, 0xfffffc00, v0
	v_mov_b64_e32 v[4:5], 0
	v_lshrrev_b32_e32 v2, 3, v2
	v_mov_b32_e32 v5, 2
	v_mov_b32_e32 v6, 1
	v_mov_b32_e32 v3, 1
	s_or_b64 exec, exec, s[6:7]
	v_and_b32_e32 v7, v3, v0
	v_ashrrev_i32_e32 v3, 31, v2
	v_bfe_u32 v147, v0, v6, 2
	v_lshl_add_u32 v0, v7, 7, v4
	s_movk_i32 s2, 0x1100
	v_lshlrev_b64 v[8:9], 2, v[2:3]
	v_mad_i64_i32 v[158:159], s[2:3], v2, s2, v[0:1]
	v_or_b32_e32 v0, v8, v147
	v_mov_b64_e32 v[10:11], s[36:37]
	v_mad_u64_u32 v[18:19], s[2:3], v0, s48, v[10:11]
	v_mov_b64_e32 v[10:11], s[38:39]
	v_mov_b64_e32 v[6:7], s[34:35]
	v_mad_i32_i24 v19, v9, s48, v19
	v_mad_u64_u32 v[20:21], s[2:3], v0, s14, v[10:11]
	v_mad_i32_i24 v21, v9, s14, v21
	v_lshl_add_u64 v[8:9], v[18:19], 0, v[120:121]
	v_lshl_add_u64 v[10:11], v[18:19], 0, v[122:123]
	v_mad_u64_u32 v[6:7], s[2:3], v158, s24, v[6:7]
	v_mul_u32_u24_e32 v0, 0x60, v147
	v_lshl_add_u64 v[8:9], v[114:115], 1, v[8:9]
	v_lshl_add_u64 v[14:15], v[116:117], 1, v[10:11]
	v_mad_i32_i24 v7, v159, s24, v7
	v_lshlrev_b32_e32 v0, 1, v0
	s_barrier
	global_load_dwordx4 v[10:13], v[8:9], off
	s_nop 0
	global_load_dwordx4 v[14:17], v[14:15], off
	v_lshl_add_u64 v[8:9], v[18:19], 0, v[124:125]
	v_lshl_add_u64 v[18:19], v[20:21], 0, v[126:127]
	v_mov_b32_e32 v145, v1
	v_lshl_add_u64 v[6:7], v[6:7], 0, v[0:1]
	v_lshl_add_u64 v[22:23], v[18:19], 0, v[144:145]
	v_lshl_add_u64 v[18:19], v[20:21], 0, v[128:129]
	v_lshl_add_u64 v[6:7], v[6:7], 0, v[112:113]
	v_mov_b32_e32 v143, v1
	v_lshl_add_u64 v[8:9], v[118:119], 1, v[8:9]
	v_lshl_add_u64 v[26:27], v[18:19], 0, v[144:145]
	v_lshl_add_u64 v[6:7], v[6:7], 0, v[142:143]
	global_load_dwordx4 v[18:21], v[8:9], off
	s_nop 0
	global_load_dwordx4 v[22:25], v[22:23], off
	s_nop 0
	global_load_dwordx4 v[26:29], v[26:27], off
	s_nop 0
	global_load_dwordx4 v[100:103], v[6:7], off
	global_load_dwordx4 v[96:99], v[6:7], off offset:32
	global_load_dwordx4 v[92:95], v[6:7], off offset:64
	global_load_dwordx4 v[88:91], v[6:7], off offset:96
	global_load_dwordx4 v[84:87], v[6:7], off offset:128
	global_load_dwordx4 v[80:83], v[6:7], off offset:160
	s_mov_b32 s2, 0x220000
	v_add_u32_e32 v38, 0x6800, v171
	v_add_u32_e32 v39, 0x7900, v171
	v_mad_i64_i32 v[30:31], s[2:3], v2, s2, v[134:135]
	v_mad_i64_i32 v[32:33], s[2:3], v2, s15, v[136:137]
	v_mad_i64_i32 v[34:35], s[2:3], v2, s15, v[138:139]
	v_mad_i64_i32 v[36:37], s[2:3], v2, s15, v[140:141]
	v_add_u32_e32 v177, 1, v5
	v_mov_b32_e32 v2, v1
	v_mov_b32_e32 v3, v1
	v_mov_b32_e32 v4, v1
	v_mov_b32_e32 v5, v1
	v_mov_b32_e32 v6, v1
	v_mov_b32_e32 v7, v1
	v_mov_b32_e32 v8, v1
	v_mov_b32_e32 v9, v1
	v_mad_u64_u32 v[160:161], s[6:7], v147, s14, v[30:31]
	v_mad_u64_u32 v[162:163], s[6:7], v147, s48, v[32:33]
	v_mad_u64_u32 v[164:165], s[6:7], v147, s48, v[34:35]
	v_mad_u64_u32 v[166:167], s[6:7], v147, s48, v[36:37]
	v_mov_b32_e32 v0, v1
	s_mov_b32 s2, 0
	v_mov_b32_e32 v143, 0
	v_mov_b32_e32 v145, 0xf149f2ca
	s_mov_b64 s[6:7], 0
	s_waitcnt vmcnt(10)
	ds_write_b128 v151, v[10:13]
	s_waitcnt vmcnt(9)
	ds_write_b128 v157, v[14:17]
	s_waitcnt vmcnt(8)
	ds_write_b128 v169, v[18:21]
	s_waitcnt vmcnt(7)
	ds_write2_b64 v38, v[22:23], v[24:25] offset1:1
	s_waitcnt vmcnt(6)
	ds_write2_b64 v39, v[26:27], v[28:29] offset1:1
	v_mov_b32_e32 v14, v1
	v_mov_b32_e32 v15, v1
	v_mov_b32_e32 v10, v1
	v_mov_b32_e32 v11, v1
	v_mov_b32_e32 v12, v1
	v_mov_b32_e32 v13, v1
	v_mov_b64_e32 v[30:31], v[14:15]
	v_mov_b64_e32 v[46:47], v[14:15]
	v_mov_b64_e32 v[28:29], v[12:13]
	v_mov_b64_e32 v[26:27], v[10:11]
	v_mov_b64_e32 v[24:25], v[8:9]
	v_mov_b64_e32 v[22:23], v[6:7]
	v_mov_b64_e32 v[20:21], v[4:5]
	v_mov_b64_e32 v[18:19], v[2:3]
	v_mov_b64_e32 v[16:17], v[0:1]
	v_mov_b64_e32 v[44:45], v[12:13]
	v_mov_b64_e32 v[42:43], v[10:11]
	v_mov_b64_e32 v[40:41], v[8:9]
	v_mov_b64_e32 v[38:39], v[6:7]
	v_mov_b64_e32 v[36:37], v[4:5]
	v_mov_b64_e32 v[34:35], v[2:3]
	v_mov_b64_e32 v[32:33], v[0:1]
	s_waitcnt lgkmcnt(0)
	s_barrier
	v_mov_b32_e32 v224, 0
	v_mov_b32_e32 v225, 0
	v_mov_b32_e32 v226, 0
	v_mov_b32_e32 v227, 0
	v_mov_b32_e32 v228, 0
	v_mov_b32_e32 v229, 0
	v_mov_b32_e32 v230, 0
	v_mov_b32_e32 v231, 0
	v_mov_b32_e32 v232, 0
	v_mov_b32_e32 v233, 0
	v_mov_b32_e32 v234, 0
	v_mov_b32_e32 v235, 0
	v_mov_b32_e32 v236, 0
	v_mov_b32_e32 v237, 0
	v_mov_b32_e32 v238, 0
	v_mov_b32_e32 v239, 0
	v_mov_b32_e32 v204, 0
	s_branch .LBB0_895
; #define MFMA(a, b, c) __builtin_amdgcn_mfma_f32_32x32x16_bf16((a), (b), (c), 0, 0, 0)
; DI unsigned pack2(float a, float b) { f32v2 v = {a, b}; return __builtin_bit_cast(unsigned, __builtin_convertvector(v, bf16v2)); }
; #define LSTORE(bf) { *(uint4*)&Ks[bf][kr0][kc0] = rk0; *(uint4*)&Ks[bf][kr1][kc1] = rk1; if (NKC == 3) *(uint4*)&Ks[bf][kr2][kc2] = rk2; \
;     *(uint2*)&Vs[bf][vd0][vk0] = make_uint2(rv0.x, rv0.y); *(uint2*)&Vs[bf][vd0][vk0 + 4] = make_uint2(rv0.z, rv0.w); \
;     *(uint2*)&Vs[bf][vd0 + 32][vk0] = make_uint2(rv1.x, rv1.y); *(uint2*)&Vs[bf][vd0 + 32][vk0 + 4] = make_uint2(rv1.z, rv1.w); }
; #define LSTORE(bf) { *(uint4*)&Ks[bf][kr0][kc0] = rk0; *(uint4*)&Ks[bf][kr1][kc1] = rk1; if (NKC == 3) *(uint4*)&Ks[bf][kr2][kc2] = rk2; \
;     *(uint2*)&Vs[bf][vd0][vk0] = make_uint2(rv0.x, rv0.y); *(uint2*)&Vs[bf][vd0][vk0 + 4] = make_uint2(rv0.z, rv0.w); \
;     *(uint2*)&Vs[bf][vd0 + 32][vk0] = make_uint2(rv1.x, rv1.y); *(uint2*)&Vs[bf][vd0 + 32][vk0 + 4] = make_uint2(rv1.z, rv1.w); }
; template <int DK, bool NA> ...
;     ...
;       float ls = 0.f;
; #pragma unroll
;       for (int kb = 0; kb < 2; kb++)
; #pragma unroll
;         for (int i = 0; i < 16; i++) { float pv = __builtin_amdgcn_exp2f(s[kb][i] - mn); s[kb][i] = pv; ls += pv; }
;       l_run += ls;
;       bf16x8 pf[2][2];
; #pragma unroll
;       for (int kb = 0; kb < 2; kb++)
; #pragma unroll
;         for (int sx = 0; sx < 2; sx++) {
;           uint4 u; u.x = pack2(s[kb][8 * sx], s[kb][8 * sx + 1]); u.y = pack2(s[kb][8 * sx + 2], s[kb][8 * sx + 3]);
;           u.z = pack2(s[kb][8 * sx + 4], s[kb][8 * sx + 5]); u.w = pack2(s[kb][8 * sx + 6], s[kb][8 * sx + 7]);
;           pf[kb][sx] = __builtin_bit_cast(bf16x8, u);
;         }
; #pragma unroll
;       for (int db = 0; db < 2; db++)
; #pragma unroll
;         for (int kb = 0; kb < 2; kb++)
; #pragma unroll
;           for (int sx = 0; sx < 2; sx++) {
;             const u16* vp = &Vs[buf][db * 32 + r][32 * kb + 16 * sx + 4 * h];
;             uint2 lo = *(const uint2*)vp, hi = *(const uint2*)(vp + 8);
;             uint4 u; u.x = lo.x; u.y = lo.y; u.z = hi.x; u.w = hi.y;
;             o[db] = MFMA(__builtin_bit_cast(bf16x8, u), pf[kb][sx], o[db]);
;           }
;     }
;     if (t + 1 < nTiles) LSTORE(buf ^ 1);
;     __syncthreads();
.LBB0_894:
	s_mul_i32 s8, s3, 0x2200
	v_add_u32_e32 v0, s8, v173
	v_add_u32_e32 v15, 0x6800, v0
	v_add_u32_e32 v0, 0x7800, v0
	ds_read2_b64 v[240:243], v15 offset0:0 offset1:2
	ds_read2_b64 v[244:247], v0 offset0:32 offset1:34
	ds_read2_b64 v[248:251], v15 offset0:4 offset1:6
	ds_read2_b64 v[178:181], v0 offset0:36 offset1:38
	v_exp_f32_e32 v64, v64
	v_exp_f32_e32 v65, v65
	v_exp_f32_e32 v66, v66
	v_exp_f32_e32 v67, v67
	v_exp_f32_e32 v68, v68
	v_exp_f32_e32 v69, v69
	v_exp_f32_e32 v70, v70
	v_exp_f32_e32 v71, v71
	v_cvt_pk_bf16_f32 v188, v64, v65
	v_cvt_pk_bf16_f32 v189, v66, v67
	v_cvt_pk_bf16_f32 v190, v68, v69
	v_cvt_pk_bf16_f32 v191, v70, v71
	v_add_f32_e32 v14, v64, v65
	v_add_f32_e32 v14, v66, v14
	v_add_f32_e32 v14, v67, v14
	v_add_f32_e32 v14, v68, v14
	v_add_f32_e32 v14, v69, v14
	v_add_f32_e32 v14, v70, v14
	v_add_f32_e32 v14, v71, v14
	ds_read2_b64 v[64:67], v15 offset0:8 offset1:10
	ds_read2_b64 v[68:71], v0 offset0:40 offset1:42
	s_waitcnt lgkmcnt(4)
	v_mfma_f32_32x32x16_bf16 v[32:47], v[240:243], v[188:191], v[32:47]
	v_mfma_f32_32x32x16_bf16 v[16:31], v[244:247], v[188:191], v[16:31]
	v_exp_f32_e32 v72, v72
	v_exp_f32_e32 v73, v73
	v_exp_f32_e32 v74, v74
	v_exp_f32_e32 v75, v75
	v_exp_f32_e32 v76, v76
	v_exp_f32_e32 v77, v77
	v_exp_f32_e32 v78, v78
	v_exp_f32_e32 v79, v79
	v_cvt_pk_bf16_f32 v192, v72, v73
	v_cvt_pk_bf16_f32 v193, v74, v75
	v_cvt_pk_bf16_f32 v194, v76, v77
	v_cvt_pk_bf16_f32 v195, v78, v79
	v_add_f32_e32 v14, v72, v14
	v_add_f32_e32 v14, v73, v14
	v_add_f32_e32 v14, v74, v14
	v_add_f32_e32 v14, v75, v14
	v_add_f32_e32 v14, v76, v14
	v_add_f32_e32 v14, v77, v14
	v_add_f32_e32 v14, v78, v14
	v_add_f32_e32 v14, v79, v14
	ds_read2_b64 v[72:75], v15 offset0:12 offset1:14
	ds_read2_b64 v[76:79], v0 offset0:44 offset1:46
	s_waitcnt lgkmcnt(4)
	v_mfma_f32_32x32x16_bf16 v[32:47], v[248:251], v[192:195], v[32:47]
	v_mfma_f32_32x32x16_bf16 v[16:31], v[178:181], v[192:195], v[16:31]
	v_exp_f32_e32 v48, v48
	v_exp_f32_e32 v49, v49
	v_exp_f32_e32 v50, v50
	v_exp_f32_e32 v51, v51
	v_exp_f32_e32 v52, v52
	v_exp_f32_e32 v53, v53
	v_exp_f32_e32 v54, v54
	v_exp_f32_e32 v55, v55
	v_cvt_pk_bf16_f32 v196, v48, v49
	v_cvt_pk_bf16_f32 v197, v50, v51
	v_cvt_pk_bf16_f32 v198, v52, v53
	v_cvt_pk_bf16_f32 v199, v54, v55
	v_add_f32_e32 v14, v48, v14
	v_add_f32_e32 v14, v49, v14
	v_add_f32_e32 v14, v50, v14
	v_add_f32_e32 v14, v51, v14
	v_add_f32_e32 v14, v52, v14
	v_add_f32_e32 v14, v53, v14
	v_add_f32_e32 v14, v54, v14
	v_add_f32_e32 v14, v55, v14
	s_waitcnt lgkmcnt(2)
	v_mfma_f32_32x32x16_bf16 v[32:47], v[64:67], v[196:199], v[32:47]
	v_mfma_f32_32x32x16_bf16 v[16:31], v[68:71], v[196:199], v[16:31]
	v_exp_f32_e32 v56, v56
	v_exp_f32_e32 v57, v57
	v_exp_f32_e32 v58, v58
	v_exp_f32_e32 v59, v59
	v_exp_f32_e32 v60, v60
	v_exp_f32_e32 v61, v61
	v_exp_f32_e32 v62, v62
	v_exp_f32_e32 v63, v63
	v_cvt_pk_bf16_f32 v200, v56, v57
	v_cvt_pk_bf16_f32 v201, v58, v59
	v_cvt_pk_bf16_f32 v202, v60, v61
	v_cvt_pk_bf16_f32 v203, v62, v63
	v_add_f32_e32 v14, v56, v14
	v_add_f32_e32 v14, v57, v14
	v_add_f32_e32 v14, v58, v14
	v_add_f32_e32 v14, v59, v14
	v_add_f32_e32 v14, v60, v14
	v_add_f32_e32 v14, v61, v14
	v_add_f32_e32 v14, v62, v14
	v_add_f32_e32 v14, v63, v14
	s_waitcnt lgkmcnt(0)
	v_mfma_f32_32x32x16_bf16 v[32:47], v[72:75], v[200:203], v[32:47]
	v_mfma_f32_32x32x16_bf16 v[16:31], v[76:79], v[200:203], v[16:31]
	v_add_f32_e32 v143, v143, v14
	s_xor_b32 s3, s3, 1
	s_mul_i32 s8, s3, 0x3400
	s_mulk_i32 s3, 0xee00
	s_add_i32 s2, s2, 1
	v_cmp_eq_u32_e32 vcc, s2, v177
	v_lshl_add_u64 v[162:163], v[162:163], 0, s[12:13]
	v_lshl_add_u64 v[164:165], v[164:165], 0, s[12:13]
	v_lshl_add_u64 v[166:167], v[166:167], 0, s[12:13]
	v_add3_u32 v0, s8, v149, v174
	s_waitcnt vmcnt(4)
	ds_write_b128 v0, v[2:5]
	v_add3_u32 v0, s8, v153, v175
	s_waitcnt vmcnt(3)
	ds_write_b128 v0, v[6:9]
	v_add3_u32 v0, s8, v168, v176
	s_add_i32 s8, s8, s3
	s_waitcnt vmcnt(2)
	ds_write_b128 v0, v[10:13]
	v_add3_u32 v0, s8, v170, v144
	s_mov_b64 s[8:9], 0x80
	v_add_u32_e32 v2, 0x6800, v0
	v_add_u32_e32 v0, 0x7900, v0
	v_lshl_add_u64 v[160:161], v[160:161], 0, s[8:9]
	s_or_b64 s[6:7], vcc, s[6:7]
	s_waitcnt vmcnt(0)
	ds_write2_b64 v2, v[104:105], v[106:107] offset1:1
	ds_write2_b64 v0, v[108:109], v[110:111] offset1:1
	s_waitcnt lgkmcnt(0)
	s_barrier
	s_andn2_b64 exec, exec, s[6:7]
	s_cbranch_execz .LBB0_897
; #define MFMA(a, b, c) __builtin_amdgcn_mfma_f32_32x32x16_bf16((a), (b), (c), 0, 0, 0)
; DI float xhalf_max(float v) { auto r = __builtin_amdgcn_permlane32_swap(__float_as_uint(v), __float_as_uint(v), false, false); return fmaxf(__uint_as_float(r[0]), __uint_as_float(r[1])); }
; #define GLOAD(t) { const int pos0_ = TILE_POS(t); \
;     rk0 = *(const uint4*)(K + (size_t)(pos0_ + kr0) * ldk + kc0); rk1 = *(const uint4*)(K + (size_t)(pos0_ + kr1) * ldk + kc1); \
;     if (NKC == 3) rk2 = *(const uint4*)(K + (size_t)(pos0_ + kr2) * ldk + kc2); \
;     rv0 = *(const uint4*)(Vt + (size_t)vd0 * SEQA + pos0_ + vk0); rv1 = *(const uint4*)(Vt + (size_t)(vd0 + 32) * SEQA + pos0_ + vk0); }
; template <int DK, bool NA> ...
;     ...
;   for (int t = 0; t < nTiles; t++) {
;     const int buf = t & 1;
;     if (t + 1 < nTiles) GLOAD(t + 1);
;     const bool win = NA && (t < nWin);
;     const int kr = rsA + t;
;     bool act = true;
;     if (win) act = (kr >= rsw) && (kr < rsw + 8);
;     if (act) {
;       f32x16 s[2];
; #pragma unroll
;       for (int kb = 0; kb < 2; kb++) {
; #pragma unroll
;         for (int i = 0; i < 16; i++) s[kb][i] = 0.f;
; #pragma unroll
;         for (int ks = 0; ks < KS; ks++) { bf16x8 a = *(const bf16x8*)&Ks[buf][kb * 32 + r][ks * 16 + h * 8]; s[kb] = MFMA(a, qf[ks], s[kb]); }
;       }
;       float mx = -1e30f;
; #pragma unroll
;       for (int kb = 0; kb < 2; kb++)
; #pragma unroll
;         for (int i = 0; i < 16; i++) {
;           float v = s[kb][i];
;           if (NA) {
;             if (win) {
;               const int kc = kb * 32 + (i & 3) + 8 * (i >> 2) + 4 * h;
;               const bool vis = (unsigned)(kc - cs) < 16u;
;               const int idx = (kr - iw + 7) * 31 + (kc - jq + 15);
;               const float bv = biasL[vis ? idx : 0];
;               v = vis ? v + bv : -1e30f;
;             }
;           }
;           s[kb][i] = v; mx = fmaxf(mx, v);
;         }
;       mx = xhalf_max(mx);
;       float mn = m_run;
;       if (__builtin_amdgcn_ballot_w64(mx > m_run) != 0) {
;         mn = fmaxf(m_run, mx);
;         const float al = __builtin_amdgcn_exp2f(m_run - mn);
;         m_run = mn; l_run *= al;
; #pragma unroll
;         for (int i = 0; i < 16; i++) { o[0][i] *= al; o[1][i] *= al; }
;       }
.LBB0_895:
	v_lshl_add_u64 v[10:11], s[96:97], 0, v[164:165]
	s_mov_b32 s8, 0x12323000
	v_add_co_u32_e32 v10, vcc, s8, v10
	v_lshl_add_u64 v[14:15], s[96:97], 0, v[160:161]
	s_nop 0
	v_addc_co_u32_e32 v11, vcc, 0, v11, vcc
	s_mov_b32 s8, 0x13ca0000
	v_add_co_u32_e32 v48, vcc, s8, v14
	s_and_b32 s3, s2, 1
	s_nop 0
	v_addc_co_u32_e32 v49, vcc, 0, v15, vcc
	s_mov_b32 s8, 0x13ce4000
	v_add_co_u32_e32 v14, vcc, s8, v14
	s_mul_i32 s8, s3, 0x3400
	v_lshl_add_u64 v[2:3], s[96:97], 0, v[162:163]
	v_lshl_add_u64 v[6:7], s[96:97], 0, v[166:167]
	v_addc_co_u32_e32 v15, vcc, 0, v15, vcc
	v_add_u32_e32 v0, s8, v172
	global_load_dwordx4 v[2:5], v[2:3], off
	s_nop 0
	global_load_dwordx4 v[6:9], v[6:7], off
	s_nop 0
	global_load_dwordx4 v[10:13], v[10:11], off
	s_nop 0
	global_load_dwordx4 v[108:111], v[14:15], off offset:128
	global_load_dwordx4 v[104:107], v[48:49], off offset:128
	ds_read_b128 v[48:51], v0
	ds_read_b128 v[52:55], v0 offset:32
	s_waitcnt vmcnt(10) lgkmcnt(1)
	v_mfma_f32_32x32x16_bf16 v[64:79], v[48:51], v[100:103], v[224:239]
	ds_read_b128 v[48:51], v0 offset:64
	ds_read_b128 v[178:181], v0 offset:6688
	s_waitcnt vmcnt(9) lgkmcnt(2)
	v_mfma_f32_32x32x16_bf16 v[64:79], v[52:55], v[96:99], v[64:79]
	s_waitcnt vmcnt(8) lgkmcnt(1)
	v_mfma_f32_32x32x16_bf16 v[64:79], v[48:51], v[92:95], v[64:79]
	ds_read_b128 v[48:51], v0 offset:96
	s_waitcnt vmcnt(7) lgkmcnt(0)
	v_mfma_f32_32x32x16_bf16 v[64:79], v[48:51], v[88:91], v[64:79]
	ds_read_b128 v[48:51], v0 offset:128
	s_waitcnt vmcnt(6) lgkmcnt(0)
	v_mfma_f32_32x32x16_bf16 v[64:79], v[48:51], v[84:87], v[64:79]
	ds_read_b128 v[48:51], v0 offset:160
	s_waitcnt vmcnt(5) lgkmcnt(0)
	v_mfma_f32_32x32x16_bf16 v[64:79], v[48:51], v[80:83], v[64:79]
	ds_read_b128 v[48:51], v0 offset:6656
	s_waitcnt lgkmcnt(0)
	v_mfma_f32_32x32x16_bf16 v[48:63], v[48:51], v[100:103], v[224:239]
	v_mfma_f32_32x32x16_bf16 v[48:63], v[178:181], v[96:99], v[48:63]
	ds_read_b128 v[178:181], v0 offset:6720
	s_waitcnt lgkmcnt(0)
	v_mfma_f32_32x32x16_bf16 v[48:63], v[178:181], v[92:95], v[48:63]
	ds_read_b128 v[178:181], v0 offset:6752
	s_waitcnt lgkmcnt(0)
	v_mfma_f32_32x32x16_bf16 v[48:63], v[178:181], v[88:91], v[48:63]
	ds_read_b128 v[178:181], v0 offset:6784
	s_waitcnt lgkmcnt(0)
	v_mfma_f32_32x32x16_bf16 v[48:63], v[178:181], v[84:87], v[48:63]
	ds_read_b128 v[178:181], v0 offset:6816
	v_max3_f32 v0, v64, s16, v65
	v_max3_f32 v0, v0, v66, v67
	v_max3_f32 v0, v0, v68, v69
	v_max3_f32 v0, v0, v70, v71
	v_max3_f32 v0, v0, v72, v73
	v_max3_f32 v0, v0, v74, v75
	s_waitcnt lgkmcnt(0)
	v_mfma_f32_32x32x16_bf16 v[48:63], v[178:181], v[80:83], v[48:63]
	v_max3_f32 v0, v0, v76, v77
	v_max3_f32 v0, v0, v78, v79
	s_nop 9
	v_max3_f32 v0, v0, v48, v49
	v_max3_f32 v0, v0, v50, v51
	v_max3_f32 v0, v0, v52, v53
	v_max3_f32 v0, v0, v54, v55
	v_max3_f32 v0, v0, v56, v57
	v_max3_f32 v0, v0, v58, v59
	v_max3_f32 v0, v0, v60, v61
	v_max3_f32 v0, v0, v62, v63
	v_mov_b32_e32 v14, v0
	s_nop 1
	v_permlane32_swap_b32_e32 v0, v14
	v_max_f32_e32 v14, v14, v14
	v_max_f32_e32 v0, v0, v0
	v_max_f32_e32 v0, v0, v14
	v_add_f32_e32 v0, v0, v204
	v_add_f32_e32 v14, 4.0, v145
	v_cmp_gt_f32_e32 vcc, v0, v14
	s_cbranch_vccz .LBB0_894
	v_max_f32_e32 v0, v0, v0
	v_max_f32_e32 v14, v145, v145
	v_max_f32_e32 v14, v14, v0
	v_sub_f32_e32 v0, v145, v14
	v_exp_f32_e32 v0, v0
	v_mov_b32_e32 v145, v14
	v_sub_f32_e32 v15, v14, v204
	v_mov_b32_e32 v204, v14
	v_sub_f32_e32 v224, 0, v14
	v_mov_b32_e32 v225, v224
	v_mov_b32_e32 v226, v224
	v_mov_b32_e32 v227, v224
	v_mov_b32_e32 v228, v224
	v_mov_b32_e32 v229, v224
	v_mov_b32_e32 v230, v224
	v_mov_b32_e32 v231, v224
	v_mov_b32_e32 v232, v224
	v_mov_b32_e32 v233, v224
	v_mov_b32_e32 v234, v224
	v_mov_b32_e32 v235, v224
	v_mov_b32_e32 v236, v224
	v_mov_b32_e32 v237, v224
	v_mov_b32_e32 v238, v224
	v_mov_b32_e32 v239, v224
	v_sub_f32_e32 v64, v64, v15
	v_sub_f32_e32 v65, v65, v15
	v_sub_f32_e32 v66, v66, v15
	v_sub_f32_e32 v67, v67, v15
	v_sub_f32_e32 v68, v68, v15
	v_sub_f32_e32 v69, v69, v15
	v_sub_f32_e32 v70, v70, v15
	v_sub_f32_e32 v71, v71, v15
	v_sub_f32_e32 v72, v72, v15
	v_sub_f32_e32 v73, v73, v15
	v_sub_f32_e32 v74, v74, v15
	v_sub_f32_e32 v75, v75, v15
	v_sub_f32_e32 v76, v76, v15
	v_sub_f32_e32 v77, v77, v15
	v_sub_f32_e32 v78, v78, v15
	v_sub_f32_e32 v79, v79, v15
	v_sub_f32_e32 v48, v48, v15
	v_sub_f32_e32 v49, v49, v15
	v_sub_f32_e32 v50, v50, v15
	v_sub_f32_e32 v51, v51, v15
	v_sub_f32_e32 v52, v52, v15
	v_sub_f32_e32 v53, v53, v15
	v_sub_f32_e32 v54, v54, v15
	v_sub_f32_e32 v55, v55, v15
	v_sub_f32_e32 v56, v56, v15
	v_sub_f32_e32 v57, v57, v15
	v_sub_f32_e32 v58, v58, v15
	v_sub_f32_e32 v59, v59, v15
	v_sub_f32_e32 v60, v60, v15
	v_sub_f32_e32 v61, v61, v15
	v_sub_f32_e32 v62, v62, v15
	v_sub_f32_e32 v63, v63, v15
	v_pk_mul_f32 v[46:47], v[46:47], v[0:1] op_sel_hi:[1,0]
	v_pk_mul_f32 v[44:45], v[44:45], v[0:1] op_sel_hi:[1,0]
	v_pk_mul_f32 v[42:43], v[42:43], v[0:1] op_sel_hi:[1,0]
	v_pk_mul_f32 v[40:41], v[40:41], v[0:1] op_sel_hi:[1,0]
	v_pk_mul_f32 v[38:39], v[38:39], v[0:1] op_sel_hi:[1,0]
	v_pk_mul_f32 v[36:37], v[36:37], v[0:1] op_sel_hi:[1,0]
	v_pk_mul_f32 v[34:35], v[34:35], v[0:1] op_sel_hi:[1,0]
	v_pk_mul_f32 v[32:33], v[32:33], v[0:1] op_sel_hi:[1,0]
	v_pk_mul_f32 v[30:31], v[30:31], v[0:1] op_sel_hi:[1,0]
	v_pk_mul_f32 v[28:29], v[28:29], v[0:1] op_sel_hi:[1,0]
	v_pk_mul_f32 v[26:27], v[26:27], v[0:1] op_sel_hi:[1,0]
	v_pk_mul_f32 v[24:25], v[24:25], v[0:1] op_sel_hi:[1,0]
	v_pk_mul_f32 v[22:23], v[22:23], v[0:1] op_sel_hi:[1,0]
	v_pk_mul_f32 v[20:21], v[20:21], v[0:1] op_sel_hi:[1,0]
	v_pk_mul_f32 v[18:19], v[18:19], v[0:1] op_sel_hi:[1,0]
	v_pk_mul_f32 v[16:17], v[16:17], v[0:1] op_sel_hi:[1,0]
	v_mul_f32_e32 v143, v143, v0
	s_branch .LBB0_894

; DI float xhalf_max(float v) { auto r = __builtin_amdgcn_permlane32_swap(__float_as_uint(v), __float_as_uint(v), false, false); return fmaxf(__uint_as_float(r[0]), __uint_as_float(r[1])); }
; template <int DK, bool NA> ...
;     ...
;       float mx = -1e30f;
; #pragma unroll
;       for (int kb = 0; kb < 2; kb++)
; #pragma unroll
;         for (int i = 0; i < 16; i++) {
;           float v = s[kb][i];
;           if (NA) {
;             if (win) {
;               const int kc = kb * 32 + (i & 3) + 8 * (i >> 2) + 4 * h;
;               const bool vis = (unsigned)(kc - cs) < 16u;
;               const int idx = (kr - iw + 7) * 31 + (kc - jq + 15);
;               const float bv = biasL[vis ? idx : 0];
;               v = vis ? v + bv : -1e30f;
;             }
;           }
;           s[kb][i] = v; mx = fmaxf(mx, v);
;         }
;       mx = xhalf_max(mx);
;       float mn = m_run;
;       if (__builtin_amdgcn_ballot_w64(mx > m_run) != 0) {
;         mn = fmaxf(m_run, mx);
;         const float al = __builtin_amdgcn_exp2f(m_run - mn);
;         m_run = mn; l_run *= al;
; #pragma unroll
;         for (int i = 0; i < 16; i++) { o[0][i] *= al; o[1][i] *= al; }
;       }
.LBB0_968:
	s_or_b64 exec, exec, s[2:3]
	v_max3_f32 v160, v50, s33, v51
	v_max3_f32 v160, v160, v52, v53
	v_max3_f32 v160, v160, v54, v55
	v_max3_f32 v160, v160, v56, v57
	v_max3_f32 v160, v160, v58, v59
	v_max3_f32 v160, v160, v60, v61
	v_max3_f32 v160, v160, v62, v63
	v_max3_f32 v160, v160, v64, v65
	v_max3_f32 v160, v160, v34, v35
	v_max3_f32 v160, v160, v36, v37
	v_max3_f32 v160, v160, v38, v39
	v_max3_f32 v160, v160, v40, v41
	v_max3_f32 v160, v160, v42, v43
	v_max3_f32 v160, v160, v44, v45
	v_max3_f32 v160, v160, v46, v47
	v_max3_f32 v160, v160, v48, v49
	v_mov_b32_e32 v161, v160
	s_nop 1
	v_permlane32_swap_b32_e32 v160, v161
	v_max_f32_e32 v161, v161, v161
	v_max_f32_e32 v160, v160, v160
	v_max_f32_e32 v160, v160, v161
	v_add_f32_e32 v161, 4.0, v159
	v_cmp_gt_f32_e32 vcc, v160, v161
	s_cbranch_vccz .LBB0_970
	v_max_f32_e32 v160, v160, v160
	v_max_f32_e32 v161, v159, v159
	v_max_f32_e32 v161, v161, v160
	v_sub_f32_e32 v159, v159, v161
	v_exp_f32_e32 v160, v159
	v_mov_b32_e32 v159, v161
	v_pk_mul_f32 v[32:33], v[32:33], v[160:161] op_sel_hi:[1,0]
	v_pk_mul_f32 v[30:31], v[30:31], v[160:161] op_sel_hi:[1,0]
	v_pk_mul_f32 v[28:29], v[28:29], v[160:161] op_sel_hi:[1,0]
	v_pk_mul_f32 v[26:27], v[26:27], v[160:161] op_sel_hi:[1,0]
	v_pk_mul_f32 v[24:25], v[24:25], v[160:161] op_sel_hi:[1,0]
	v_pk_mul_f32 v[22:23], v[22:23], v[160:161] op_sel_hi:[1,0]
	v_pk_mul_f32 v[20:21], v[20:21], v[160:161] op_sel_hi:[1,0]
	v_pk_mul_f32 v[18:19], v[18:19], v[160:161] op_sel_hi:[1,0]
	v_pk_mul_f32 v[16:17], v[16:17], v[160:161] op_sel_hi:[1,0]
	v_pk_mul_f32 v[14:15], v[14:15], v[160:161] op_sel_hi:[1,0]
	v_pk_mul_f32 v[12:13], v[12:13], v[160:161] op_sel_hi:[1,0]
	v_pk_mul_f32 v[10:11], v[10:11], v[160:161] op_sel_hi:[1,0]
	v_pk_mul_f32 v[8:9], v[8:9], v[160:161] op_sel_hi:[1,0]
	v_pk_mul_f32 v[6:7], v[6:7], v[160:161] op_sel_hi:[1,0]
	v_pk_mul_f32 v[4:5], v[4:5], v[160:161] op_sel_hi:[1,0]
	v_pk_mul_f32 v[2:3], v[2:3], v[160:161] op_sel_hi:[1,0]
	v_mul_f32_e32 v133, v133, v160

; #define MFMA(a, b, c) __builtin_amdgcn_mfma_f32_32x32x16_bf16((a), (b), (c), 0, 0, 0)
; DI float xhalf_max(float v) { auto r = __builtin_amdgcn_permlane32_swap(__float_as_uint(v), __float_as_uint(v), false, false); return fmaxf(__uint_as_float(r[0]), __uint_as_float(r[1])); }
; #define GLOAD(t) { const int pos0_ = TILE_POS(t); \
;     rk0 = *(const uint4*)(K + (size_t)(pos0_ + kr0) * ldk + kc0); rk1 = *(const uint4*)(K + (size_t)(pos0_ + kr1) * ldk + kc1); \
;     if (NKC == 3) rk2 = *(const uint4*)(K + (size_t)(pos0_ + kr2) * ldk + kc2); \
;     rv0 = *(const uint4*)(Vt + (size_t)vd0 * SEQA + pos0_ + vk0); rv1 = *(const uint4*)(Vt + (size_t)(vd0 + 32) * SEQA + pos0_ + vk0); }
; template <int DK, bool NA> ...
;     ...
;   for (int t = 0; t < nTiles; t++) {
;     const int buf = t & 1;
;     if (t + 1 < nTiles) GLOAD(t + 1);
;     const bool win = NA && (t < nWin);
;     const int kr = rsA + t;
;     bool act = true;
;     if (win) act = (kr >= rsw) && (kr < rsw + 8);
;     if (act) {
;       f32x16 s[2];
; #pragma unroll
;       for (int kb = 0; kb < 2; kb++) {
; #pragma unroll
;         for (int i = 0; i < 16; i++) s[kb][i] = 0.f;
; #pragma unroll
;         for (int ks = 0; ks < KS; ks++) { bf16x8 a = *(const bf16x8*)&Ks[buf][kb * 32 + r][ks * 16 + h * 8]; s[kb] = MFMA(a, qf[ks], s[kb]); }
;       }
;       float mx = -1e30f;
; #pragma unroll
;       for (int kb = 0; kb < 2; kb++)
; #pragma unroll
;         for (int i = 0; i < 16; i++) {
;           float v = s[kb][i];
;           if (NA) {
;             if (win) {
;               const int kc = kb * 32 + (i & 3) + 8 * (i >> 2) + 4 * h;
;               const bool vis = (unsigned)(kc - cs) < 16u;
;               const int idx = (kr - iw + 7) * 31 + (kc - jq + 15);
;               const float bv = biasL[vis ? idx : 0];
;               v = vis ? v + bv : -1e30f;
;             }
;           }
;           s[kb][i] = v; mx = fmaxf(mx, v);
;         }
;       mx = xhalf_max(mx);
;       float mn = m_run;
;       if (__builtin_amdgcn_ballot_w64(mx > m_run) != 0) {
;         mn = fmaxf(m_run, mx);
;         const float al = __builtin_amdgcn_exp2f(m_run - mn);
;         m_run = mn; l_run *= al;
; #pragma unroll
;         for (int i = 0; i < 16; i++) { o[0][i] *= al; o[1][i] *= al; }
;       }
.LBB0_1021:
	v_lshl_add_u64 v[34:35], s[96:97], 0, v[132:133]
	global_load_dwordx4 v[82:85], v[34:35], off
	v_lshl_add_u64 v[34:35], s[96:97], 0, v[134:135]
	global_load_dwordx4 v[86:89], v[34:35], off
	v_lshl_add_u64 v[34:35], s[96:97], 0, v[130:131]
	v_add_co_u32_e32 v36, vcc, 0xf020000, v34
	s_and_b32 s3, s2, 1
	s_nop 0
	v_addc_co_u32_e32 v37, vcc, 0, v35, vcc
	v_add_co_u32_e32 v34, vcc, 0xf064000, v34
	s_mul_i32 s8, s3, 0x2400
	s_nop 0
	v_addc_co_u32_e32 v35, vcc, 0, v35, vcc
	v_add_u32_e32 v146, s8, v142
	global_load_dwordx4 v[90:93], v[36:37], off offset:128
	global_load_dwordx4 v[94:97], v[34:35], off offset:128
	ds_read_b128 v[34:37], v146
	ds_read_b128 v[38:41], v146 offset:32
	s_waitcnt lgkmcnt(1)
	v_mfma_f32_32x32x16_bf16 v[50:65], v[34:37], v[78:81], 0
	ds_read_b128 v[34:37], v146 offset:64
	ds_read_b128 v[158:161], v146 offset:4640
	s_waitcnt lgkmcnt(2)
	v_mfma_f32_32x32x16_bf16 v[50:65], v[38:41], v[74:77], v[50:65]
	s_waitcnt lgkmcnt(1)
	v_mfma_f32_32x32x16_bf16 v[50:65], v[34:37], v[70:73], v[50:65]
	ds_read_b128 v[34:37], v146 offset:96
	s_waitcnt lgkmcnt(0)
	v_mfma_f32_32x32x16_bf16 v[50:65], v[34:37], v[66:69], v[50:65]
	ds_read_b128 v[34:37], v146 offset:4608
	s_waitcnt lgkmcnt(0)
	v_mfma_f32_32x32x16_bf16 v[34:49], v[34:37], v[78:81], 0
	v_mfma_f32_32x32x16_bf16 v[34:49], v[158:161], v[74:77], v[34:49]
	ds_read_b128 v[158:161], v146 offset:4672
	s_waitcnt lgkmcnt(0)
	v_mfma_f32_32x32x16_bf16 v[34:49], v[158:161], v[70:73], v[34:49]
	ds_read_b128 v[158:161], v146 offset:4704
	s_nop 3
	v_max3_f32 v146, v50, s13, v51
	v_max3_f32 v146, v146, v52, v53
	v_max3_f32 v146, v146, v54, v55
	v_max3_f32 v146, v146, v56, v57
	v_max3_f32 v146, v146, v58, v59
	v_max3_f32 v146, v146, v60, v61
	s_waitcnt lgkmcnt(0)
	v_mfma_f32_32x32x16_bf16 v[34:49], v[158:161], v[66:69], v[34:49]
	v_max3_f32 v146, v146, v62, v63
	v_max3_f32 v146, v146, v64, v65
	s_nop 9
	v_max3_f32 v146, v146, v34, v35
	v_max3_f32 v146, v146, v36, v37
	v_max3_f32 v146, v146, v38, v39
	v_max3_f32 v146, v146, v40, v41
	v_max3_f32 v146, v146, v42, v43
	v_max3_f32 v146, v146, v44, v45
	v_max3_f32 v146, v146, v46, v47
	v_max3_f32 v146, v146, v48, v49
	v_mov_b32_e32 v147, v146
	s_nop 1
	v_permlane32_swap_b32_e32 v146, v147
	v_max_f32_e32 v147, v147, v147
	v_max_f32_e32 v146, v146, v146
	v_max_f32_e32 v146, v146, v147
	v_add_f32_e32 v147, 4.0, v123
	v_cmp_gt_f32_e32 vcc, v146, v147
	s_cbranch_vccz .LBB0_1020
	v_max_f32_e32 v146, v146, v146
	v_max_f32_e32 v147, v123, v123
	v_max_f32_e32 v147, v147, v146
	v_sub_f32_e32 v123, v123, v147
	v_exp_f32_e32 v146, v123
	v_mov_b32_e32 v123, v147
	v_pk_mul_f32 v[32:33], v[32:33], v[146:147] op_sel_hi:[1,0]
	v_pk_mul_f32 v[30:31], v[30:31], v[146:147] op_sel_hi:[1,0]
	v_pk_mul_f32 v[28:29], v[28:29], v[146:147] op_sel_hi:[1,0]
	v_pk_mul_f32 v[26:27], v[26:27], v[146:147] op_sel_hi:[1,0]
	v_pk_mul_f32 v[24:25], v[24:25], v[146:147] op_sel_hi:[1,0]
	v_pk_mul_f32 v[22:23], v[22:23], v[146:147] op_sel_hi:[1,0]
	v_pk_mul_f32 v[20:21], v[20:21], v[146:147] op_sel_hi:[1,0]
	v_pk_mul_f32 v[18:19], v[18:19], v[146:147] op_sel_hi:[1,0]
	v_pk_mul_f32 v[16:17], v[16:17], v[146:147] op_sel_hi:[1,0]
	v_pk_mul_f32 v[14:15], v[14:15], v[146:147] op_sel_hi:[1,0]
	v_pk_mul_f32 v[12:13], v[12:13], v[146:147] op_sel_hi:[1,0]
	v_pk_mul_f32 v[10:11], v[10:11], v[146:147] op_sel_hi:[1,0]
	v_pk_mul_f32 v[8:9], v[8:9], v[146:147] op_sel_hi:[1,0]
	v_pk_mul_f32 v[6:7], v[6:7], v[146:147] op_sel_hi:[1,0]
	v_pk_mul_f32 v[4:5], v[4:5], v[146:147] op_sel_hi:[1,0]
	v_pk_mul_f32 v[2:3], v[2:3], v[146:147] op_sel_hi:[1,0]
	v_mul_f32_e32 v121, v121, v146
	s_branch .LBB0_1020
.LBB0_1023:
	s_or_b64 exec, exec, s[6:7]
	v_and_b32_e32 v82, 1, v125
	v_mad_u32_u24 v83, v82, s12, v142
	ds_read_b128 v[34:37], v83
	ds_read_b128 v[38:41], v83 offset:32
	s_waitcnt lgkmcnt(1)
	v_mfma_f32_32x32x16_bf16 v[50:65], v[34:37], v[78:81], 0
	ds_read_b128 v[34:37], v83 offset:64
	s_waitcnt lgkmcnt(1)
	v_mfma_f32_32x32x16_bf16 v[50:65], v[38:41], v[74:77], v[50:65]
	s_waitcnt lgkmcnt(0)
	v_mfma_f32_32x32x16_bf16 v[50:65], v[34:37], v[70:73], v[50:65]
	ds_read_b128 v[34:37], v83 offset:96
	s_waitcnt lgkmcnt(0)
	v_mfma_f32_32x32x16_bf16 v[50:65], v[34:37], v[66:69], v[50:65]
	ds_read_b128 v[34:37], v83 offset:4608
	s_waitcnt lgkmcnt(0)
	v_mfma_f32_32x32x16_bf16 v[34:49], v[34:37], v[78:81], 0
	ds_read_b128 v[78:81], v83 offset:4640
	s_waitcnt lgkmcnt(0)
	v_mfma_f32_32x32x16_bf16 v[34:49], v[78:81], v[74:77], v[34:49]
	ds_read_b128 v[74:77], v83 offset:4672
	s_waitcnt lgkmcnt(0)
	v_mfma_f32_32x32x16_bf16 v[34:49], v[74:77], v[70:73], v[34:49]
	ds_read_b128 v[70:73], v83 offset:4704
	s_waitcnt lgkmcnt(0)
	v_mfma_f32_32x32x16_bf16 v[34:49], v[70:73], v[66:69], v[34:49]
	v_max3_f32 v66, v50, s13, v51
	v_max3_f32 v66, v66, v52, v53
	v_max3_f32 v66, v66, v54, v55
	v_max3_f32 v66, v66, v56, v57
	v_max3_f32 v66, v66, v58, v59
	v_max3_f32 v66, v66, v60, v61
	v_max3_f32 v66, v66, v62, v63
	v_max3_f32 v66, v66, v64, v65
	s_nop 3
	v_max3_f32 v66, v66, v34, v35
	v_max3_f32 v66, v66, v36, v37
	v_max3_f32 v66, v66, v38, v39
	v_max3_f32 v66, v66, v40, v41
	v_max3_f32 v66, v66, v42, v43
	v_max3_f32 v66, v66, v44, v45
	v_max3_f32 v66, v66, v46, v47
	v_max3_f32 v66, v66, v48, v49
	v_mov_b32_e32 v67, v66
	s_nop 1
	v_permlane32_swap_b32_e32 v66, v67
	v_max_f32_e32 v67, v67, v67
	v_max_f32_e32 v66, v66, v66
	v_max_f32_e32 v66, v66, v67
	v_add_f32_e32 v67, 4.0, v123
	v_cmp_gt_f32_e32 vcc, v66, v67
	s_cbranch_vccz .LBB0_1025
	v_max_f32_e32 v66, v66, v66
	v_max_f32_e32 v67, v123, v123
	v_max_f32_e32 v67, v67, v66
	v_sub_f32_e32 v66, v123, v67
	v_exp_f32_e32 v66, v66
	v_mov_b32_e32 v123, v67
	v_pk_mul_f32 v[32:33], v[32:33], v[66:67] op_sel_hi:[1,0]
	v_pk_mul_f32 v[30:31], v[30:31], v[66:67] op_sel_hi:[1,0]
	v_pk_mul_f32 v[28:29], v[28:29], v[66:67] op_sel_hi:[1,0]
	v_pk_mul_f32 v[26:27], v[26:27], v[66:67] op_sel_hi:[1,0]
	v_pk_mul_f32 v[24:25], v[24:25], v[66:67] op_sel_hi:[1,0]
	v_pk_mul_f32 v[22:23], v[22:23], v[66:67] op_sel_hi:[1,0]
	v_pk_mul_f32 v[20:21], v[20:21], v[66:67] op_sel_hi:[1,0]
	v_pk_mul_f32 v[18:19], v[18:19], v[66:67] op_sel_hi:[1,0]
	v_pk_mul_f32 v[16:17], v[16:17], v[66:67] op_sel_hi:[1,0]
	v_pk_mul_f32 v[14:15], v[14:15], v[66:67] op_sel_hi:[1,0]
	v_pk_mul_f32 v[12:13], v[12:13], v[66:67] op_sel_hi:[1,0]
	v_pk_mul_f32 v[10:11], v[10:11], v[66:67] op_sel_hi:[1,0]
	v_pk_mul_f32 v[8:9], v[8:9], v[66:67] op_sel_hi:[1,0]
	v_pk_mul_f32 v[6:7], v[6:7], v[66:67] op_sel_hi:[1,0]
	v_pk_mul_f32 v[4:5], v[4:5], v[66:67] op_sel_hi:[1,0]
	v_pk_mul_f32 v[2:3], v[2:3], v[66:67] op_sel_hi:[1,0]
	v_mul_f32_e32 v121, v121, v66
